# GEMM K-loops: half-step software pipeline (LDS fragment reads issued ahead, LDS-DMA interleaved with MFMAs)
# speedup vs baseline: 1.0230x; 1.0230x over previous
.LBB0_41:
	s_nop 1
	v_sub_co_u32_e64 v0, s[16:17], s3, 64
	s_and_b64 s[16:17], s[16:17], exec
	v_readfirstlane_b32 s8, v0
	v_mov_b32_e32 v80, v220
	s_cselect_b32 s8, s3, s8
	s_cselect_b32 s10, 0, 8
	v_ashrrev_i32_e32 v16, 6, v80
	s_bfe_u32 s17, s8, 0x50003
	v_bfe_u32 v17, v80, 3, 3
	v_lshlrev_b32_e32 v18, 5, v16
	v_bfe_u32 v19, v80, 4, 2
	s_add_i32 s18, s8, s10
	s_lshl_b32 s8, s17, 7
	v_or_b32_e32 v1, v18, v17
	v_xor_b32_e32 v0, v19, v80
	v_add_u32_e32 v2, s8, v1
	s_movk_i32 s13, 0xb00
	v_lshlrev_b32_e32 v0, 3, v0
	s_lshl_b32 s19, s17, 13
	s_lshl_b32 s42, s18, 10
	v_mul_lo_u32 v2, v2, s13
	v_and_b32_e32 v20, 56, v0
	v_or_b32_e32 v3, 8, v1
	s_sub_i32 s10, s42, s19
	v_or_b32_e32 v192, v2, v20
	v_lshrrev_b32_e32 v2, 1, v3
	s_or_b32 s10, s10, s31
	v_xor_b32_e32 v2, v2, v80
	v_add_u32_e32 v4, s8, v3
	v_lshlrev_b32_e32 v2, 3, v2
	v_add_u32_e32 v3, s10, v3
	v_mul_lo_u32 v4, v4, s13
	v_and_b32_e32 v21, 56, v2
	v_mul_lo_u32 v3, v3, s13
	v_or_b32_e32 v2, v21, v4
	v_or_b32_e32 v4, v21, v3
	v_or_b32_e32 v3, 16, v1
	v_add_u32_e32 v5, s8, v3
	v_add_u32_e32 v3, s10, v3
	v_add_u32_e32 v0, s10, v1
	v_mul_lo_u32 v3, v3, s13
	v_or_b32_e32 v1, 24, v1
	v_or_b32_e32 v8, v3, v20
	v_lshrrev_b32_e32 v3, 1, v1
	v_mul_lo_u32 v5, v5, s13
	v_xor_b32_e32 v3, v3, v80
	v_or_b32_e32 v6, v5, v20
	v_add_u32_e32 v5, s8, v1
	v_lshlrev_b32_e32 v3, 3, v3
	v_add_u32_e32 v1, s10, v1
	s_cmp_lg_u32 32, -1
	v_and_b32_e32 v22, 56, v3
	v_mul_lo_u32 v1, v1, s13
	v_lshlrev_b32_e32 v23, 12, v16
	s_cselect_b32 s43, 32, 0
	v_ashrrev_i32_e32 v3, 1, v80
	v_or_b32_e32 v12, v22, v1
	v_add_u32_e32 v82, s43, v23
	v_and_b32_e32 v1, 15, v80
	v_and_b32_e32 v81, 0xffffffc0, v3
	s_add_i32 s44, s43, 0x4000
	v_mul_lo_u32 v0, v0, s13
	v_or_b32_e32 v24, v81, v1
	v_lshlrev_b32_e32 v1, 7, v80
	v_add_u32_e32 v3, s44, v23
	v_readfirstlane_b32 s44, v82
	v_readlane_b32 s88, v252, 11
	v_or_b32_e32 v0, v0, v20
	v_and_b32_e32 v83, 0x2780, v1
	v_lshl_add_u64 v[14:15], v[192:193], 1, s[28:29]
	s_mov_b32 m0, s44
	v_mov_b32_e32 v1, v193
	v_readlane_b32 s89, v252, 12
	v_readfirstlane_b32 s44, v3
	global_load_lds_dwordx4 v[14:15], off
	v_lshl_add_u64 v[0:1], v[0:1], 1, s[88:89]
	s_mov_b32 m0, s44
	v_mov_b32_e32 v3, v193
	s_add_i32 s44, s43, 0x400
	global_load_lds_dwordx4 v[0:1], off
	v_lshl_add_u64 v[0:1], v[2:3], 1, s[28:29]
	v_add_u32_e32 v2, s44, v23
	v_mul_lo_u32 v5, v5, s13
	v_readfirstlane_b32 s44, v2
	s_mov_b32 m0, s44
	s_add_i32 s44, s43, 0x4400
	v_add_u32_e32 v2, s44, v23
	global_load_lds_dwordx4 v[0:1], off
	v_readfirstlane_b32 s44, v2
	s_mov_b32 m0, s44
	s_add_i32 s44, s43, 0x800
	v_or_b32_e32 v10, v22, v5
	v_mov_b32_e32 v5, v193
	v_add_u32_e32 v2, s44, v23
	v_lshl_add_u64 v[0:1], v[4:5], 1, s[88:89]
	v_readfirstlane_b32 s44, v2
	global_load_lds_dwordx4 v[0:1], off
	s_mov_b32 m0, s44
	s_add_i32 s44, s43, 0x4800
	v_mov_b32_e32 v7, v193
	v_add_u32_e32 v2, s44, v23
	v_lshl_add_u64 v[0:1], v[6:7], 1, s[28:29]
	v_readfirstlane_b32 s44, v2
	global_load_lds_dwordx4 v[0:1], off
	s_mov_b32 m0, s44
	s_add_i32 s44, s43, 0xc00
	v_mov_b32_e32 v9, v193
	v_add_u32_e32 v2, s44, v23
	s_addk_i32 s43, 0x4c00
	v_lshl_add_u64 v[0:1], v[8:9], 1, s[88:89]
	v_mov_b32_e32 v11, v193
	v_readfirstlane_b32 s44, v2
	v_add_u32_e32 v2, s43, v23
	global_load_lds_dwordx4 v[0:1], off
	v_lshl_add_u64 v[0:1], v[10:11], 1, s[28:29]
	s_mov_b32 m0, s44
	v_mov_b32_e32 v13, v193
	v_readfirstlane_b32 s43, v2
	global_load_lds_dwordx4 v[0:1], off
	v_lshl_add_u64 v[0:1], v[12:13], 1, s[88:89]
	s_mov_b32 m0, s43
	s_mov_b32 s9, 0x16000
	global_load_lds_dwordx4 v[0:1], off
	v_bfe_u32 v0, v80, 1, 3
	v_xor_b32_e32 v1, v19, v0
	v_bitop3_b32 v0, v19, v0, 4 bitop3:0x36
	v_lshlrev_b32_e32 v84, 4, v0
	v_or_b32_e32 v0, s8, v17
	v_add_u32_e32 v0, v0, v18
	v_mul_lo_u32 v0, v0, s13
	v_lshlrev_b32_e32 v86, 4, v1
	v_or_b32_e32 v192, v0, v20
	s_mul_i32 s43, s17, 0x58000
	v_mul_lo_u32 v0, v16, s9
	v_mul_u32_u24_e32 v1, 0xb00, v17
	v_add3_u32 v2, v0, s43, v1
	v_or_b32_e32 v2, v2, v21
	s_add_i32 s44, s43, 0xb000
	v_lshl_add_u64 v[64:65], v[192:193], 1, s[40:41]
	v_add_u32_e32 v192, 0x5800, v2
	v_add3_u32 v2, s44, v0, v1
	s_add_i32 s43, s43, 0x10800
	v_lshl_add_u64 v[66:67], v[192:193], 1, s[40:41]
	v_or_b32_e32 v192, v2, v20
	v_add3_u32 v2, s43, v0, v1
	s_or_b32 s42, s42, s31
	v_lshl_add_u64 v[68:69], v[192:193], 1, s[40:41]
	v_or_b32_e32 v192, v2, v22
	v_add3_u32 v2, s42, v17, v18
	v_subrev_u32_e32 v2, s19, v2
	s_mul_i32 s18, s18, 0x2c0000
	v_readlane_b32 s9, v254, 28
	v_mul_lo_u32 v2, v2, s13
	s_add_i32 s19, s9, s18
	v_lshl_add_u64 v[70:71], v[192:193], 1, s[40:41]
	v_or_b32_e32 v192, v2, v20
	v_readlane_b32 s14, v254, 26
	v_add_u32_e32 v2, s19, v0
	v_readlane_b32 s9, v254, 29
	v_readlane_b32 s15, v254, 27
	v_add3_u32 v2, v2, v1, v21
	s_mul_i32 s17, s17, 0x1600000
	s_add_i32 s19, s9, s18
	v_readlane_b32 s9, v254, 30
	v_lshl_add_u64 v[72:73], v[192:193], 1, s[14:15]
	v_subrev_u32_e32 v192, s17, v2
	v_add_u32_e32 v2, s19, v0
	s_add_i32 s18, s9, s18
	v_add3_u32 v2, v2, v1, v20
	v_add_u32_e32 v0, s18, v0
	s_waitcnt vmcnt(0)
	v_lshl_add_u64 v[74:75], v[192:193], 1, s[14:15]
	v_subrev_u32_e32 v192, s17, v2
	v_add3_u32 v0, v0, v1, v22
	v_lshl_add_u64 v[76:77], v[192:193], 1, s[14:15]
	v_subrev_u32_e32 v192, s17, v0
	v_mov_b32_e32 v0, 0
	s_mov_b32 s16, 0
	v_lshlrev_b32_e32 v85, 7, v24
	v_lshl_add_u64 v[78:79], v[192:193], 1, s[14:15]
	s_mov_b64 s[42:43], 0
	v_mov_b32_e32 v1, v0
	v_mov_b32_e32 v2, v0
	v_mov_b32_e32 v3, v0
	v_mov_b32_e32 v4, v0
	v_mov_b32_e32 v5, v0
	v_mov_b32_e32 v6, v0
	v_mov_b32_e32 v7, v0
	v_mov_b32_e32 v8, v0
	v_mov_b32_e32 v9, v0
	v_mov_b32_e32 v10, v0
	v_mov_b32_e32 v11, v0
	v_mov_b32_e32 v12, v0
	v_mov_b32_e32 v13, v0
	v_mov_b32_e32 v14, v0
	v_mov_b32_e32 v15, v0
	v_mov_b32_e32 v16, v0
	v_mov_b32_e32 v17, v0
	v_mov_b32_e32 v18, v0
	v_mov_b32_e32 v19, v0
	v_mov_b32_e32 v20, v0
	v_mov_b32_e32 v21, v0
	v_mov_b32_e32 v22, v0
	v_mov_b32_e32 v23, v0
	v_mov_b32_e32 v24, v0
	v_mov_b32_e32 v25, v0
	v_mov_b32_e32 v26, v0
	v_mov_b32_e32 v27, v0
	v_mov_b32_e32 v28, v0
	v_mov_b32_e32 v29, v0
	v_mov_b32_e32 v30, v0
	v_mov_b32_e32 v31, v0
	v_mov_b32_e32 v32, v0
	v_mov_b32_e32 v33, v0
	v_mov_b32_e32 v34, v0
	v_mov_b32_e32 v35, v0
	v_mov_b32_e32 v36, v0
	v_mov_b32_e32 v37, v0
	v_mov_b32_e32 v38, v0
	v_mov_b32_e32 v39, v0
	v_mov_b32_e32 v40, v0
	v_mov_b32_e32 v41, v0
	v_mov_b32_e32 v42, v0
	v_mov_b32_e32 v43, v0
	v_mov_b32_e32 v44, v0
	v_mov_b32_e32 v45, v0
	v_mov_b32_e32 v46, v0
	v_mov_b32_e32 v47, v0
	v_mov_b32_e32 v48, v0
	v_mov_b32_e32 v49, v0
	v_mov_b32_e32 v50, v0
	v_mov_b32_e32 v51, v0
	v_mov_b32_e32 v52, v0
	v_mov_b32_e32 v53, v0
	v_mov_b32_e32 v54, v0
	v_mov_b32_e32 v55, v0
	v_mov_b32_e32 v56, v0
	v_mov_b32_e32 v57, v0
	v_mov_b32_e32 v58, v0
	v_mov_b32_e32 v59, v0
	v_mov_b32_e32 v60, v0
	v_mov_b32_e32 v61, v0
	v_mov_b32_e32 v62, v0
	v_mov_b32_e32 v63, v0
	v_readlane_b32 s90, v252, 13
	v_readlane_b32 s91, v252, 14
	v_readlane_b32 s92, v252, 15
	v_readlane_b32 s93, v252, 16
	v_readlane_b32 s94, v252, 17
	v_readlane_b32 s95, v252, 18
	s_waitcnt vmcnt(0) lgkmcnt(0)
	s_barrier
	v_add_u32_e32 v134, 32, v85
	v_add_u32_e32 v135, 32, v83
	v_add_u32_e32 v132, v134, v86
	v_add_u32_e32 v133, v135, v86
	ds_read_b128 v[88:91], v132
	ds_read_b128 v[96:99], v132 offset:2048
	ds_read_b128 v[104:107], v132 offset:4096
	ds_read_b128 v[112:115], v132 offset:6144
	ds_read_b128 v[92:95], v133 offset:16384
	ds_read_b128 v[100:103], v133 offset:18432
	ds_read_b128 v[108:111], v133 offset:20480
	ds_read_b128 v[116:119], v133 offset:22528
	v_add_u32_e32 v128, 0x8000, v82
	s_nop 0
	v_readfirstlane_b32 s18, v128
	s_nop 1
	v_lshl_add_u64 v[130:131], v[64:65], 0, s[42:43]
	s_mov_b32 m0, s18
	s_nop 0
	global_load_lds_dwordx4 v[130:131], off
	v_lshl_add_u64 v[130:131], v[72:73], 0, s[42:43]
	s_add_i32 m0, s18, 0x4000
	s_nop 0
	global_load_lds_dwordx4 v[130:131], off
	v_lshl_add_u64 v[130:131], v[66:67], 0, s[42:43]
	s_add_i32 m0, s18, 0x400
	s_nop 0
	global_load_lds_dwordx4 v[130:131], off
	v_lshl_add_u64 v[130:131], v[74:75], 0, s[42:43]
	s_add_i32 m0, s18, 0x4400
	s_nop 0
	global_load_lds_dwordx4 v[130:131], off
	v_lshl_add_u64 v[130:131], v[68:69], 0, s[42:43]
	s_add_i32 m0, s18, 0x800
	s_nop 0
	global_load_lds_dwordx4 v[130:131], off
	v_lshl_add_u64 v[130:131], v[76:77], 0, s[42:43]
	s_add_i32 m0, s18, 0x4800
	s_nop 0
	global_load_lds_dwordx4 v[130:131], off
	v_lshl_add_u64 v[130:131], v[70:71], 0, s[42:43]
	s_add_i32 m0, s18, 0xc00
	s_nop 0
	global_load_lds_dwordx4 v[130:131], off
	v_lshl_add_u64 v[130:131], v[78:79], 0, s[42:43]
	s_add_i32 m0, s18, 0x4c00
	s_nop 0
	global_load_lds_dwordx4 v[130:131], off
	s_add_u32 s42, s42, 0x80
	s_addc_u32 s43, s43, 0
.Lg42_loop:
	s_and_b32 s17, s16, 0x8000
	s_xor_b32 s18, s17, 0x8000
	v_add_u32_e32 v132, v134, v84
	v_add_u32_e32 v133, v135, v84
	ds_read_b128 v[152:155], v132
	ds_read_b128 v[156:159], v132 offset:2048
	ds_read_b128 v[160:163], v132 offset:4096
	ds_read_b128 v[164:167], v132 offset:6144
	s_waitcnt lgkmcnt(4)
	v_mfma_f32_16x16x32_bf16 v[60:63], v[88:91], v[92:95], v[60:63]
	v_mfma_f32_16x16x32_bf16 v[56:59], v[88:91], v[100:103], v[56:59]
	v_mfma_f32_16x16x32_bf16 v[52:55], v[88:91], v[108:111], v[52:55]
	v_mfma_f32_16x16x32_bf16 v[48:51], v[88:91], v[116:119], v[48:51]
	ds_read_b128 v[168:171], v133 offset:16384
	ds_read_b128 v[172:175], v133 offset:18432
	ds_read_b128 v[176:179], v133 offset:20480
	ds_read_b128 v[180:183], v133 offset:22528
	v_mfma_f32_16x16x32_bf16 v[44:47], v[96:99], v[92:95], v[44:47]
	v_mfma_f32_16x16x32_bf16 v[40:43], v[96:99], v[100:103], v[40:43]
	v_mfma_f32_16x16x32_bf16 v[36:39], v[96:99], v[108:111], v[36:39]
	v_mfma_f32_16x16x32_bf16 v[32:35], v[96:99], v[116:119], v[32:35]
	v_mfma_f32_16x16x32_bf16 v[28:31], v[104:107], v[92:95], v[28:31]
	v_mfma_f32_16x16x32_bf16 v[24:27], v[104:107], v[100:103], v[24:27]
	v_mfma_f32_16x16x32_bf16 v[20:23], v[104:107], v[108:111], v[20:23]
	v_mfma_f32_16x16x32_bf16 v[16:19], v[104:107], v[116:119], v[16:19]
	v_mfma_f32_16x16x32_bf16 v[12:15], v[112:115], v[92:95], v[12:15]
	v_mfma_f32_16x16x32_bf16 v[8:11], v[112:115], v[100:103], v[8:11]
	v_mfma_f32_16x16x32_bf16 v[4:7], v[112:115], v[108:111], v[4:7]
	v_mfma_f32_16x16x32_bf16 v[0:3], v[112:115], v[116:119], v[0:3]
	s_waitcnt vmcnt(0) lgkmcnt(0)
	s_barrier
	v_add_u32_e32 v128, s17, v82
	s_add_i32 s17, s18, 32
	v_add_u32_e32 v134, s17, v85
	v_add_u32_e32 v135, s17, v83
	v_add_u32_e32 v132, v134, v86
	v_add_u32_e32 v133, v135, v86
	ds_read_b128 v[88:91], v132
	ds_read_b128 v[96:99], v132 offset:2048
	ds_read_b128 v[104:107], v132 offset:4096
	ds_read_b128 v[112:115], v132 offset:6144
	ds_read_b128 v[92:95], v133 offset:16384
	ds_read_b128 v[100:103], v133 offset:18432
	ds_read_b128 v[108:111], v133 offset:20480
	ds_read_b128 v[116:119], v133 offset:22528
	v_readfirstlane_b32 s18, v128
	v_mfma_f32_16x16x32_bf16 v[60:63], v[152:155], v[168:171], v[60:63]
	v_lshl_add_u64 v[130:131], v[64:65], 0, s[42:43]
	s_mov_b32 m0, s18
	s_nop 0
	global_load_lds_dwordx4 v[130:131], off
	v_mfma_f32_16x16x32_bf16 v[56:59], v[152:155], v[172:175], v[56:59]
	v_mfma_f32_16x16x32_bf16 v[52:55], v[152:155], v[176:179], v[52:55]
	v_lshl_add_u64 v[130:131], v[72:73], 0, s[42:43]
	s_add_i32 m0, s18, 0x4000
	s_nop 0
	global_load_lds_dwordx4 v[130:131], off
	v_mfma_f32_16x16x32_bf16 v[48:51], v[152:155], v[180:183], v[48:51]
	v_mfma_f32_16x16x32_bf16 v[44:47], v[156:159], v[168:171], v[44:47]
	v_lshl_add_u64 v[130:131], v[66:67], 0, s[42:43]
	s_add_i32 m0, s18, 0x400
	s_nop 0
	global_load_lds_dwordx4 v[130:131], off
	v_mfma_f32_16x16x32_bf16 v[40:43], v[156:159], v[172:175], v[40:43]
	v_mfma_f32_16x16x32_bf16 v[36:39], v[156:159], v[176:179], v[36:39]
	v_lshl_add_u64 v[130:131], v[74:75], 0, s[42:43]
	s_add_i32 m0, s18, 0x4400
	s_nop 0
	global_load_lds_dwordx4 v[130:131], off
	v_mfma_f32_16x16x32_bf16 v[32:35], v[156:159], v[180:183], v[32:35]
	v_mfma_f32_16x16x32_bf16 v[28:31], v[160:163], v[168:171], v[28:31]
	v_lshl_add_u64 v[130:131], v[68:69], 0, s[42:43]
	s_add_i32 m0, s18, 0x800
	s_nop 0
	global_load_lds_dwordx4 v[130:131], off
	v_mfma_f32_16x16x32_bf16 v[24:27], v[160:163], v[172:175], v[24:27]
	v_mfma_f32_16x16x32_bf16 v[20:23], v[160:163], v[176:179], v[20:23]
	v_lshl_add_u64 v[130:131], v[76:77], 0, s[42:43]
	s_add_i32 m0, s18, 0x4800
	s_nop 0
	global_load_lds_dwordx4 v[130:131], off
	v_mfma_f32_16x16x32_bf16 v[16:19], v[160:163], v[180:183], v[16:19]
	v_mfma_f32_16x16x32_bf16 v[12:15], v[164:167], v[168:171], v[12:15]
	v_lshl_add_u64 v[130:131], v[70:71], 0, s[42:43]
	s_add_i32 m0, s18, 0xc00
	s_nop 0
	global_load_lds_dwordx4 v[130:131], off
	v_mfma_f32_16x16x32_bf16 v[8:11], v[164:167], v[172:175], v[8:11]
	v_mfma_f32_16x16x32_bf16 v[4:7], v[164:167], v[176:179], v[4:7]
	v_lshl_add_u64 v[130:131], v[78:79], 0, s[42:43]
	s_add_i32 m0, s18, 0x4c00
	s_nop 0
	global_load_lds_dwordx4 v[130:131], off
	v_mfma_f32_16x16x32_bf16 v[0:3], v[164:167], v[180:183], v[0:3]
	s_add_i32 s16, s16, 0x8000
	s_add_u32 s42, s42, 0x80
	s_addc_u32 s43, s43, 0
	s_cmpk_lg_i32 s42, 0x1580
	s_cbranch_scc1 .Lg42_loop
	s_and_b32 s17, s16, 0x8000
	s_xor_b32 s18, s17, 0x8000
	v_add_u32_e32 v132, v134, v84
	v_add_u32_e32 v133, v135, v84
	ds_read_b128 v[152:155], v132
	ds_read_b128 v[156:159], v132 offset:2048
	ds_read_b128 v[160:163], v132 offset:4096
	ds_read_b128 v[164:167], v132 offset:6144
	s_waitcnt lgkmcnt(4)
	v_mfma_f32_16x16x32_bf16 v[60:63], v[88:91], v[92:95], v[60:63]
	v_mfma_f32_16x16x32_bf16 v[56:59], v[88:91], v[100:103], v[56:59]
	v_mfma_f32_16x16x32_bf16 v[52:55], v[88:91], v[108:111], v[52:55]
	v_mfma_f32_16x16x32_bf16 v[48:51], v[88:91], v[116:119], v[48:51]
	ds_read_b128 v[168:171], v133 offset:16384
	ds_read_b128 v[172:175], v133 offset:18432
	ds_read_b128 v[176:179], v133 offset:20480
	ds_read_b128 v[180:183], v133 offset:22528
	v_mfma_f32_16x16x32_bf16 v[44:47], v[96:99], v[92:95], v[44:47]
	v_mfma_f32_16x16x32_bf16 v[40:43], v[96:99], v[100:103], v[40:43]
	v_mfma_f32_16x16x32_bf16 v[36:39], v[96:99], v[108:111], v[36:39]
	v_mfma_f32_16x16x32_bf16 v[32:35], v[96:99], v[116:119], v[32:35]
	v_mfma_f32_16x16x32_bf16 v[28:31], v[104:107], v[92:95], v[28:31]
	v_mfma_f32_16x16x32_bf16 v[24:27], v[104:107], v[100:103], v[24:27]
	v_mfma_f32_16x16x32_bf16 v[20:23], v[104:107], v[108:111], v[20:23]
	v_mfma_f32_16x16x32_bf16 v[16:19], v[104:107], v[116:119], v[16:19]
	v_mfma_f32_16x16x32_bf16 v[12:15], v[112:115], v[92:95], v[12:15]
	v_mfma_f32_16x16x32_bf16 v[8:11], v[112:115], v[100:103], v[8:11]
	v_mfma_f32_16x16x32_bf16 v[4:7], v[112:115], v[108:111], v[4:7]
	v_mfma_f32_16x16x32_bf16 v[0:3], v[112:115], v[116:119], v[0:3]
	s_waitcnt vmcnt(0) lgkmcnt(0)
	s_barrier
	v_mfma_f32_16x16x32_bf16 v[60:63], v[152:155], v[168:171], v[60:63]
	v_mfma_f32_16x16x32_bf16 v[56:59], v[152:155], v[172:175], v[56:59]
	v_mfma_f32_16x16x32_bf16 v[52:55], v[152:155], v[176:179], v[52:55]
	v_mfma_f32_16x16x32_bf16 v[48:51], v[152:155], v[180:183], v[48:51]
	v_mfma_f32_16x16x32_bf16 v[44:47], v[156:159], v[168:171], v[44:47]
	v_mfma_f32_16x16x32_bf16 v[40:43], v[156:159], v[172:175], v[40:43]
	v_mfma_f32_16x16x32_bf16 v[36:39], v[156:159], v[176:179], v[36:39]
	v_mfma_f32_16x16x32_bf16 v[32:35], v[156:159], v[180:183], v[32:35]
	v_mfma_f32_16x16x32_bf16 v[28:31], v[160:163], v[168:171], v[28:31]
	v_mfma_f32_16x16x32_bf16 v[24:27], v[160:163], v[172:175], v[24:27]
	v_mfma_f32_16x16x32_bf16 v[20:23], v[160:163], v[176:179], v[20:23]
	v_mfma_f32_16x16x32_bf16 v[16:19], v[160:163], v[180:183], v[16:19]
	v_mfma_f32_16x16x32_bf16 v[12:15], v[164:167], v[168:171], v[12:15]
	v_mfma_f32_16x16x32_bf16 v[8:11], v[164:167], v[172:175], v[8:11]
	v_mfma_f32_16x16x32_bf16 v[4:7], v[164:167], v[176:179], v[4:7]
	v_mfma_f32_16x16x32_bf16 v[0:3], v[164:167], v[180:183], v[0:3]
	v_add_u32_e32 v82, 32, v85
	v_add_u32_e32 v83, 32, v83
	v_add_u32_e32 v85, v82, v86
	ds_read_b128 v[64:67], v85 offset:32768
	v_add_u32_e32 v98, v83, v86
	ds_read_b128 v[72:75], v85 offset:34816
	ds_read_b128 v[86:89], v85 offset:36864
	ds_read_b128 v[94:97], v85 offset:38912
	ds_read_b128 v[90:93], v98 offset:53248
	ds_read_b128 v[68:71], v98 offset:49152
	ds_read_b128 v[76:79], v98 offset:51200
	ds_read_b128 v[98:101], v98 offset:55296
	s_waitcnt lgkmcnt(3)
	v_mfma_f32_16x16x32_bf16 v[52:55], v[64:67], v[90:93], v[52:55]
	s_add_i32 s3, s3, s2
	s_cmpk_gt_u32 s3, 0x7f
	v_mfma_f32_16x16x32_bf16 v[36:39], v[72:75], v[90:93], v[36:39]
	v_mfma_f32_16x16x32_bf16 v[20:23], v[86:89], v[90:93], v[20:23]
	v_mfma_f32_16x16x32_bf16 v[4:7], v[94:97], v[90:93], v[4:7]
	v_add_u32_e32 v90, v82, v84
	s_waitcnt lgkmcnt(2)
	v_mfma_f32_16x16x32_bf16 v[60:63], v[64:67], v[68:71], v[60:63]
	s_waitcnt lgkmcnt(1)
	v_mfma_f32_16x16x32_bf16 v[56:59], v[64:67], v[76:79], v[56:59]
	s_waitcnt lgkmcnt(0)
	v_mfma_f32_16x16x32_bf16 v[48:51], v[64:67], v[98:101], v[48:51]
	v_mfma_f32_16x16x32_bf16 v[44:47], v[72:75], v[68:71], v[44:47]
	v_mfma_f32_16x16x32_bf16 v[40:43], v[72:75], v[76:79], v[40:43]
	v_mfma_f32_16x16x32_bf16 v[32:35], v[72:75], v[98:101], v[32:35]
	v_mfma_f32_16x16x32_bf16 v[28:31], v[86:89], v[68:71], v[28:31]
	v_mfma_f32_16x16x32_bf16 v[24:27], v[86:89], v[76:79], v[24:27]
	v_mfma_f32_16x16x32_bf16 v[16:19], v[86:89], v[98:101], v[16:19]
	v_mfma_f32_16x16x32_bf16 v[12:15], v[94:97], v[68:71], v[12:15]
	v_mfma_f32_16x16x32_bf16 v[8:11], v[94:97], v[76:79], v[8:11]
	v_mfma_f32_16x16x32_bf16 v[0:3], v[94:97], v[98:101], v[0:3]
	ds_read_b128 v[64:67], v90 offset:32768
	v_add_u32_e32 v94, v83, v84
	ds_read_b128 v[72:75], v90 offset:34816
	ds_read_b128 v[82:85], v90 offset:36864
	ds_read_b128 v[90:93], v90 offset:38912
	ds_read_b128 v[68:71], v94 offset:49152
	ds_read_b128 v[76:79], v94 offset:51200
	ds_read_b128 v[86:89], v94 offset:53248
	ds_read_b128 v[94:97], v94 offset:55296
	s_waitcnt lgkmcnt(3)
	v_mfma_f32_16x16x32_bf16 v[60:63], v[64:67], v[68:71], v[60:63]
	s_waitcnt vmcnt(0)
	s_waitcnt lgkmcnt(0)
	s_barrier
	v_mfma_f32_16x16x32_bf16 v[56:59], v[64:67], v[76:79], v[56:59]
	s_nop 4
	v_cvt_pk_bf16_f32 v60, v60, v61
	v_cvt_pk_bf16_f32 v61, v62, v63
	v_mfma_f32_16x16x32_bf16 v[52:55], v[64:67], v[86:89], v[52:55]
	v_mfma_f32_16x16x32_bf16 v[48:51], v[64:67], v[94:97], v[48:51]
	v_and_b32_e32 v65, 0x4f, v80
	v_or_b32_e32 v66, s10, v65
	v_add_u32_e32 v64, s8, v81
	v_mfma_f32_16x16x32_bf16 v[12:15], v[90:93], v[68:71], v[12:15]
	v_ashrrev_i32_e32 v67, 31, v66
	v_ashrrev_i32_e32 v65, 31, v64
	v_lshlrev_b64 v[64:65], 1, v[64:65]
	v_mfma_f32_16x16x32_bf16 v[44:47], v[72:75], v[68:71], v[44:47]
	v_mfma_f32_16x16x32_bf16 v[28:31], v[82:85], v[68:71], v[28:31]
	v_lshlrev_b64 v[68:69], 11, v[66:67]
	v_lshl_add_u64 v[68:69], s[72:73], 0, v[68:69]
	v_lshrrev_b32_e32 v67, 1, v80
	v_lshl_add_u64 v[68:69], v[68:69], 0, v[64:65]
	v_and_b32_e32 v192, 24, v67
	v_lshl_add_u64 v[68:69], v[68:69], 0, v[192:193]
	v_cvt_pk_bf16_f32 v12, v12, v13
	v_cvt_pk_bf16_f32 v13, v14, v15
	global_store_dwordx2 v[68:69], v[12:13], off offset:96
	v_or_b32_e32 v12, 16, v66
	v_mfma_f32_16x16x32_bf16 v[8:11], v[90:93], v[76:79], v[8:11]
	v_ashrrev_i32_e32 v13, 31, v12
	v_lshlrev_b64 v[12:13], 11, v[12:13]
	v_lshl_add_u64 v[12:13], s[72:73], 0, v[12:13]
	v_lshl_add_u64 v[12:13], v[12:13], 0, v[64:65]
	v_lshl_add_u64 v[12:13], v[12:13], 0, v[192:193]
	s_nop 2
	v_cvt_pk_bf16_f32 v8, v8, v9
	v_cvt_pk_bf16_f32 v9, v10, v11
	global_store_dwordx2 v[12:13], v[8:9], off offset:96
	v_or_b32_e32 v8, 32, v66
	v_mfma_f32_16x16x32_bf16 v[4:7], v[90:93], v[86:89], v[4:7]
	v_ashrrev_i32_e32 v9, 31, v8
	v_lshlrev_b64 v[8:9], 11, v[8:9]
	v_lshl_add_u64 v[8:9], s[72:73], 0, v[8:9]
	v_lshl_add_u64 v[8:9], v[8:9], 0, v[64:65]
	v_lshl_add_u64 v[8:9], v[8:9], 0, v[192:193]
	s_nop 2
	v_cvt_pk_bf16_f32 v4, v4, v5
	v_cvt_pk_bf16_f32 v5, v6, v7
	global_store_dwordx2 v[8:9], v[4:5], off offset:96
	v_or_b32_e32 v4, 48, v66
	v_ashrrev_i32_e32 v5, 31, v4
	v_mfma_f32_16x16x32_bf16 v[40:43], v[72:75], v[76:79], v[40:43]
	v_lshlrev_b64 v[4:5], 11, v[4:5]
	v_lshl_add_u64 v[4:5], s[72:73], 0, v[4:5]
	v_lshl_add_u64 v[4:5], v[4:5], 0, v[64:65]
	v_mfma_f32_16x16x32_bf16 v[36:39], v[72:75], v[86:89], v[36:39]
	v_cvt_pk_bf16_f32 v14, v56, v57
	v_cvt_pk_bf16_f32 v15, v58, v59
	v_cvt_pk_bf16_f32 v10, v52, v53
	v_mfma_f32_16x16x32_bf16 v[32:35], v[72:75], v[94:97], v[32:35]
	v_cvt_pk_bf16_f32 v11, v54, v55
	v_lshl_add_u64 v[4:5], v[4:5], 0, v[192:193]
	v_cvt_pk_bf16_f32 v6, v48, v49
	v_mfma_f32_16x16x32_bf16 v[24:27], v[82:85], v[76:79], v[24:27]
	v_cvt_pk_bf16_f32 v7, v50, v51
	global_store_dwordx2 v[12:13], v[14:15], off
	v_cvt_pk_bf16_f32 v14, v40, v41
	v_mfma_f32_16x16x32_bf16 v[20:23], v[82:85], v[86:89], v[20:23]
	v_cvt_pk_bf16_f32 v15, v42, v43
	global_store_dwordx2 v[8:9], v[10:11], off
	v_cvt_pk_bf16_f32 v10, v36, v37
	v_mfma_f32_16x16x32_bf16 v[16:19], v[82:85], v[94:97], v[16:19]
	v_cvt_pk_bf16_f32 v11, v38, v39
	global_store_dwordx2 v[4:5], v[6:7], off
	v_cvt_pk_bf16_f32 v6, v32, v33
	v_mfma_f32_16x16x32_bf16 v[0:3], v[90:93], v[94:97], v[0:3]
	v_cvt_pk_bf16_f32 v7, v34, v35
	v_cvt_pk_bf16_f32 v44, v44, v45
	v_cvt_pk_bf16_f32 v45, v46, v47
	v_cvt_pk_bf16_f32 v28, v28, v29
	v_cvt_pk_bf16_f32 v29, v30, v31
	global_store_dwordx2 v[12:13], v[14:15], off offset:32
	v_cvt_pk_bf16_f32 v14, v24, v25
	v_cvt_pk_bf16_f32 v15, v26, v27
	global_store_dwordx2 v[8:9], v[10:11], off offset:32
	v_cvt_pk_bf16_f32 v10, v20, v21
	v_cvt_pk_bf16_f32 v11, v22, v23
	global_store_dwordx2 v[4:5], v[6:7], off offset:32
	v_cvt_pk_bf16_f32 v6, v16, v17
	v_cvt_pk_bf16_f32 v7, v18, v19
	v_cvt_pk_bf16_f32 v0, v0, v1
	v_cvt_pk_bf16_f32 v1, v2, v3
	global_store_dwordx2 v[68:69], v[60:61], off
	global_store_dwordx2 v[68:69], v[44:45], off offset:32
	global_store_dwordx2 v[68:69], v[28:29], off offset:64
	global_store_dwordx2 v[12:13], v[14:15], off offset:64
	global_store_dwordx2 v[8:9], v[10:11], off offset:64
	global_store_dwordx2 v[4:5], v[6:7], off offset:64
	global_store_dwordx2 v[4:5], v[0:1], off offset:96
	s_cbranch_scc0 .LBB0_41

.LBB0_63:
	s_min_i32 s8, s12, 8
	s_mul_i32 s42, s8, 44
	s_mov_b32 s19, s16
	s_add_i32 s18, s18, 8
	s_add_i32 s12, s12, -8
	s_add_i32 s17, s17, -8
	s_sub_i32 s16, s16, s42
	s_cmp_ge_i32 s19, s42
	s_cbranch_scc1 .LBB0_63
	s_lshl_b32 s12, s8, 3
	s_abs_i32 s16, s12
	v_cvt_f32_u32_e32 v0, s16
	s_sub_i32 s44, 0, s16
	s_abs_i32 s43, s19
	s_xor_b32 s42, s19, s12
	v_rcp_iflag_f32_e32 v0, v0
	s_ashr_i32 s42, s42, 31
	v_mov_b32_e32 v80, v220
	v_mul_f32_e32 v0, 0x4f7ffffe, v0
	v_cvt_u32_f32_e32 v0, v0
	v_ashrrev_i32_e32 v16, 6, v80
	v_bfe_u32 v19, v80, 4, 2
	v_bfe_u32 v17, v80, 3, 3
	v_readfirstlane_b32 s45, v0
	s_mul_i32 s44, s44, s45
	s_mul_hi_u32 s44, s45, s44
	s_add_i32 s45, s45, s44
	s_mul_hi_u32 s44, s43, s45
	s_mul_i32 s45, s44, s16
	s_sub_i32 s43, s43, s45
	s_add_i32 s46, s44, 1
	s_sub_i32 s45, s43, s16
	s_cmp_ge_u32 s43, s16
	s_cselect_b32 s44, s46, s44
	s_cselect_b32 s43, s45, s43
	s_add_i32 s45, s44, 1
	s_cmp_ge_u32 s43, s16
	s_cselect_b32 s43, s45, s44
	s_abs_i32 s44, s8
	v_cvt_f32_u32_e32 v0, s44
	s_xor_b32 s43, s43, s42
	s_sub_i32 s45, 0, s44
	s_sub_i32 s46, s43, s42
	v_rcp_iflag_f32_e32 v0, v0
	s_mul_i32 s12, s46, s12
	s_sub_i32 s12, s19, s12
	s_abs_i32 s48, s12
	v_mul_f32_e32 v0, 0x4f7ffffe, v0
	v_cvt_u32_f32_e32 v0, v0
	s_xor_b32 s47, s12, s8
	s_ashr_i32 s47, s47, 31
	v_lshlrev_b32_e32 v18, 5, v16
	v_readfirstlane_b32 s49, v0
	s_mul_i32 s45, s45, s49
	s_mul_hi_u32 s45, s49, s45
	s_add_i32 s49, s49, s45
	s_mul_hi_u32 s45, s48, s49
	s_mul_i32 s49, s45, s44
	s_sub_i32 s48, s48, s49
	s_add_i32 s50, s45, 1
	s_sub_i32 s49, s48, s44
	s_cmp_ge_u32 s48, s44
	s_cselect_b32 s45, s50, s45
	s_cselect_b32 s48, s49, s48
	s_add_i32 s49, s45, 1
	s_cmp_ge_u32 s48, s44
	s_cselect_b32 s44, s49, s45
	s_xor_b32 s44, s44, s47
	s_sub_i32 s45, s44, s47
	s_mul_i32 s8, s45, s8
	s_add_i32 s12, s12, s18
	s_sub_i32 s12, s12, s8
	s_lshl_b32 s8, s46, 10
	s_lshl_b32 s45, s45, 7
	v_xor_b32_e32 v0, v19, v80
	s_add_i32 s8, s45, s8
	v_or_b32_e32 v1, v18, v17
	v_lshlrev_b32_e32 v0, 3, v0
	v_add_u32_e32 v2, s8, v1
	v_and_b32_e32 v20, 56, v0
	v_or_b32_e32 v3, 8, v1
	v_lshl_or_b32 v192, v2, 10, v20
	v_lshrrev_b32_e32 v2, 1, v3
	s_lshl_b32 s12, s12, 10
	v_readlane_b32 s9, v252, 39
	v_xor_b32_e32 v2, v2, v80
	s_or_b32 s12, s12, s9
	v_lshlrev_b32_e32 v2, 3, v2
	v_add_u32_e32 v4, s8, v3
	v_and_b32_e32 v21, 56, v2
	v_add_u32_e32 v3, s12, v3
	v_lshl_or_b32 v2, v4, 10, v21
	v_lshl_or_b32 v4, v3, 10, v21
	v_or_b32_e32 v3, 16, v1
	v_add_u32_e32 v0, s12, v1
	v_add_u32_e32 v5, s8, v3
	v_add_u32_e32 v3, s12, v3
	v_or_b32_e32 v1, 24, v1
	v_lshl_or_b32 v8, v3, 10, v20
	v_lshrrev_b32_e32 v3, 1, v1
	v_xor_b32_e32 v3, v3, v80
	s_cmp_lg_u32 32, -1
	v_lshlrev_b32_e32 v3, 3, v3
	v_lshlrev_b32_e32 v23, 12, v16
	s_cselect_b32 s45, 32, 0
	v_lshl_or_b32 v6, v5, 10, v20
	v_add_u32_e32 v5, s8, v1
	v_and_b32_e32 v22, 56, v3
	v_add_u32_e32 v1, s12, v1
	v_add_u32_e32 v82, s45, v23
	v_ashrrev_i32_e32 v3, 1, v80
	s_add_i32 s46, s45, 0x4000
	v_lshl_or_b32 v12, v1, 10, v22
	v_and_b32_e32 v1, 15, v80
	v_and_b32_e32 v81, 0xffffffc0, v3
	v_add_u32_e32 v3, s46, v23
	v_readfirstlane_b32 s46, v82
	v_lshl_or_b32 v0, v0, 10, v20
	v_or_b32_e32 v24, v81, v1
	v_lshl_add_u64 v[14:15], v[192:193], 1, s[28:29]
	s_mov_b32 m0, s46
	v_mov_b32_e32 v1, v193
	v_readfirstlane_b32 s46, v3
	global_load_lds_dwordx4 v[14:15], off
	v_lshl_add_u64 v[0:1], v[0:1], 1, s[74:75]
	s_mov_b32 m0, s46
	v_mov_b32_e32 v3, v193
	s_add_i32 s46, s45, 0x400
	global_load_lds_dwordx4 v[0:1], off
	v_lshl_add_u64 v[0:1], v[2:3], 1, s[28:29]
	v_add_u32_e32 v2, s46, v23
	v_lshl_or_b32 v10, v5, 10, v22
	v_readfirstlane_b32 s46, v2
	s_mov_b32 m0, s46
	s_add_i32 s46, s45, 0x4400
	v_add_u32_e32 v2, s46, v23
	global_load_lds_dwordx4 v[0:1], off
	v_readfirstlane_b32 s46, v2
	s_mov_b32 m0, s46
	s_add_i32 s46, s45, 0x800
	v_mov_b32_e32 v5, v193
	v_add_u32_e32 v2, s46, v23
	v_lshl_add_u64 v[0:1], v[4:5], 1, s[74:75]
	v_readfirstlane_b32 s46, v2
	global_load_lds_dwordx4 v[0:1], off
	s_mov_b32 m0, s46
	s_add_i32 s46, s45, 0x4800
	v_mov_b32_e32 v7, v193
	v_add_u32_e32 v2, s46, v23
	v_lshl_add_u64 v[0:1], v[6:7], 1, s[28:29]
	v_readfirstlane_b32 s46, v2
	global_load_lds_dwordx4 v[0:1], off
	s_mov_b32 m0, s46
	s_add_i32 s46, s45, 0xc00
	v_mov_b32_e32 v9, v193
	v_add_u32_e32 v2, s46, v23
	s_addk_i32 s45, 0x4c00
	v_lshl_add_u64 v[0:1], v[8:9], 1, s[74:75]
	v_mov_b32_e32 v11, v193
	v_readfirstlane_b32 s46, v2
	v_add_u32_e32 v2, s45, v23
	global_load_lds_dwordx4 v[0:1], off
	v_lshl_add_u64 v[0:1], v[10:11], 1, s[28:29]
	s_mov_b32 m0, s46
	v_mov_b32_e32 v13, v193
	v_readfirstlane_b32 s45, v2
	global_load_lds_dwordx4 v[0:1], off
	v_lshl_add_u64 v[0:1], v[12:13], 1, s[74:75]
	s_mov_b32 m0, s45
	s_lshl_b32 s45, s43, 10
	global_load_lds_dwordx4 v[0:1], off
	v_bfe_u32 v0, v80, 1, 3
	s_lshl_b32 s46, s44, 7
	v_xor_b32_e32 v1, v19, v0
	v_bitop3_b32 v0, v19, v0, 4 bitop3:0x36
	s_add_i32 s46, s46, s45
	v_lshlrev_b32_e32 v83, 4, v0
	v_or_b32_e32 v0, s46, v17
	v_add_u32_e32 v0, v0, v18
	s_lshl_b32 s45, s47, 7
	v_subrev_u32_e32 v0, s45, v0
	s_lshl_b32 s45, s42, 10
	v_subrev_u32_e32 v0, s45, v0
	s_lshl_b32 s45, s43, 20
	s_lshl_b32 s46, s44, 17
	v_lshl_or_b32 v192, v0, 10, v20
	v_lshlrev_b32_e32 v0, 15, v16
	s_add_i32 s45, s45, s46
	v_lshlrev_b32_e32 v84, 4, v1
	v_lshlrev_b32_e32 v1, 10, v17
	v_add_u32_e32 v2, s45, v0
	v_or_b32_e32 v2, v2, v1
	s_add_i32 s18, s19, s18
	s_lshl_b32 s19, s42, 3
	v_or3_b32 v3, v2, v21, s33
	s_lshl_b32 s45, s47, 17
	s_add_i32 s47, s47, s19
	v_subrev_u32_e32 v3, s45, v3
	s_lshl_b32 s46, s42, 20
	s_sub_i32 s19, s47, s44
	s_lshl_b32 s42, s43, 3
	v_lshl_add_u64 v[64:65], v[192:193], 1, s[40:41]
	v_subrev_u32_e32 v192, s46, v3
	v_or3_b32 v3, v2, v20, s68
	s_sub_i32 s19, s19, s42
	s_min_i32 s17, s17, 8
	v_subrev_u32_e32 v3, s45, v3
	v_or3_b32 v2, v2, v22, s67
	s_mul_i32 s19, s19, s17
	v_lshl_add_u64 v[66:67], v[192:193], 1, s[40:41]
	v_subrev_u32_e32 v192, s46, v3
	v_subrev_u32_e32 v2, s45, v2
	s_add_i32 s18, s18, s19
	v_lshl_add_u64 v[68:69], v[192:193], 1, s[40:41]
	v_subrev_u32_e32 v192, s46, v2
	v_add_u32_e32 v2, s31, v17
	s_lshl_b32 s17, s18, 10
	v_add3_u32 v2, v2, v18, s17
	v_lshl_add_u64 v[70:71], v[192:193], 1, s[40:41]
	v_lshl_or_b32 v192, v2, 10, v20
	v_add3_u32 v2, s58, v0, v1
	s_lshl_b32 s17, s18, 20
	v_lshl_add_u64 v[72:73], v[192:193], 1, s[56:57]
	v_add3_u32 v192, v2, v21, s17
	v_add3_u32 v2, s59, v0, v1
	v_readlane_b32 s9, v254, 34
	s_waitcnt vmcnt(0)
	v_lshl_add_u64 v[74:75], v[192:193], 1, s[56:57]
	v_add3_u32 v192, v2, v20, s17
	v_add3_u32 v0, s9, v0, v1
	v_lshlrev_b32_e32 v25, 7, v80
	v_lshl_add_u64 v[76:77], v[192:193], 1, s[56:57]
	v_add3_u32 v192, v0, v22, s17
	v_mov_b32_e32 v0, 0
	s_mov_b32 s16, 0
	v_lshlrev_b32_e32 v85, 7, v24
	v_and_b32_e32 v86, 0x2780, v25
	v_lshl_add_u64 v[78:79], v[192:193], 1, s[56:57]
	s_mov_b64 s[42:43], 0
	v_mov_b32_e32 v1, v0
	v_mov_b32_e32 v2, v0
	v_mov_b32_e32 v3, v0
	v_mov_b32_e32 v4, v0
	v_mov_b32_e32 v5, v0
	v_mov_b32_e32 v6, v0
	v_mov_b32_e32 v7, v0
	v_mov_b32_e32 v8, v0
	v_mov_b32_e32 v9, v0
	v_mov_b32_e32 v10, v0
	v_mov_b32_e32 v11, v0
	v_mov_b32_e32 v12, v0
	v_mov_b32_e32 v13, v0
	v_mov_b32_e32 v14, v0
	v_mov_b32_e32 v15, v0
	v_mov_b32_e32 v16, v0
	v_mov_b32_e32 v17, v0
	v_mov_b32_e32 v18, v0
	v_mov_b32_e32 v19, v0
	v_mov_b32_e32 v20, v0
	v_mov_b32_e32 v21, v0
	v_mov_b32_e32 v22, v0
	v_mov_b32_e32 v23, v0
	v_mov_b32_e32 v24, v0
	v_mov_b32_e32 v25, v0
	v_mov_b32_e32 v26, v0
	v_mov_b32_e32 v27, v0
	v_mov_b32_e32 v28, v0
	v_mov_b32_e32 v29, v0
	v_mov_b32_e32 v30, v0
	v_mov_b32_e32 v31, v0
	v_mov_b32_e32 v32, v0
	v_mov_b32_e32 v33, v0
	v_mov_b32_e32 v34, v0
	v_mov_b32_e32 v35, v0
	v_mov_b32_e32 v36, v0
	v_mov_b32_e32 v37, v0
	v_mov_b32_e32 v38, v0
	v_mov_b32_e32 v39, v0
	v_mov_b32_e32 v40, v0
	v_mov_b32_e32 v41, v0
	v_mov_b32_e32 v42, v0
	v_mov_b32_e32 v43, v0
	v_mov_b32_e32 v44, v0
	v_mov_b32_e32 v45, v0
	v_mov_b32_e32 v46, v0
	v_mov_b32_e32 v47, v0
	v_mov_b32_e32 v48, v0
	v_mov_b32_e32 v49, v0
	v_mov_b32_e32 v50, v0
	v_mov_b32_e32 v51, v0
	v_mov_b32_e32 v52, v0
	v_mov_b32_e32 v53, v0
	v_mov_b32_e32 v54, v0
	v_mov_b32_e32 v55, v0
	v_mov_b32_e32 v56, v0
	v_mov_b32_e32 v57, v0
	v_mov_b32_e32 v58, v0
	v_mov_b32_e32 v59, v0
	v_mov_b32_e32 v60, v0
	v_mov_b32_e32 v61, v0
	v_mov_b32_e32 v62, v0
	v_mov_b32_e32 v63, v0
	s_waitcnt vmcnt(0) lgkmcnt(0)
	s_barrier
	v_add_u32_e32 v134, 32, v85
	v_add_u32_e32 v135, 32, v86
	v_add_u32_e32 v132, v134, v84
	v_add_u32_e32 v133, v135, v84
	ds_read_b128 v[88:91], v132
	ds_read_b128 v[96:99], v132 offset:2048
	ds_read_b128 v[104:107], v132 offset:4096
	ds_read_b128 v[112:115], v132 offset:6144
	ds_read_b128 v[92:95], v133 offset:16384
	ds_read_b128 v[100:103], v133 offset:18432
	ds_read_b128 v[108:111], v133 offset:20480
	ds_read_b128 v[116:119], v133 offset:22528
	v_add_u32_e32 v128, 0x8000, v82
	s_nop 0
	v_readfirstlane_b32 s18, v128
	s_nop 1
	v_lshl_add_u64 v[130:131], v[64:65], 0, s[42:43]
	s_mov_b32 m0, s18
	s_nop 0
	global_load_lds_dwordx4 v[130:131], off
	v_lshl_add_u64 v[130:131], v[72:73], 0, s[42:43]
	s_add_i32 m0, s18, 0x4000
	s_nop 0
	global_load_lds_dwordx4 v[130:131], off
	v_lshl_add_u64 v[130:131], v[66:67], 0, s[42:43]
	s_add_i32 m0, s18, 0x400
	s_nop 0
	global_load_lds_dwordx4 v[130:131], off
	v_lshl_add_u64 v[130:131], v[74:75], 0, s[42:43]
	s_add_i32 m0, s18, 0x4400
	s_nop 0
	global_load_lds_dwordx4 v[130:131], off
	v_lshl_add_u64 v[130:131], v[68:69], 0, s[42:43]
	s_add_i32 m0, s18, 0x800
	s_nop 0
	global_load_lds_dwordx4 v[130:131], off
	v_lshl_add_u64 v[130:131], v[76:77], 0, s[42:43]
	s_add_i32 m0, s18, 0x4800
	s_nop 0
	global_load_lds_dwordx4 v[130:131], off
	v_lshl_add_u64 v[130:131], v[70:71], 0, s[42:43]
	s_add_i32 m0, s18, 0xc00
	s_nop 0
	global_load_lds_dwordx4 v[130:131], off
	v_lshl_add_u64 v[130:131], v[78:79], 0, s[42:43]
	s_add_i32 m0, s18, 0x4c00
	s_nop 0
	global_load_lds_dwordx4 v[130:131], off
	s_add_u32 s42, s42, 0x80
	s_addc_u32 s43, s43, 0
.Lg65_loop:
	s_and_b32 s17, s16, 0x8000
	s_xor_b32 s18, s17, 0x8000
	v_add_u32_e32 v132, v134, v83
	v_add_u32_e32 v133, v135, v83
	ds_read_b128 v[152:155], v132
	ds_read_b128 v[156:159], v132 offset:2048
	ds_read_b128 v[160:163], v132 offset:4096
	ds_read_b128 v[164:167], v132 offset:6144
	s_waitcnt lgkmcnt(4)
	v_mfma_f32_16x16x32_bf16 v[60:63], v[88:91], v[92:95], v[60:63]
	v_mfma_f32_16x16x32_bf16 v[56:59], v[88:91], v[100:103], v[56:59]
	v_mfma_f32_16x16x32_bf16 v[52:55], v[88:91], v[108:111], v[52:55]
	v_mfma_f32_16x16x32_bf16 v[48:51], v[88:91], v[116:119], v[48:51]
	ds_read_b128 v[168:171], v133 offset:16384
	ds_read_b128 v[172:175], v133 offset:18432
	ds_read_b128 v[176:179], v133 offset:20480
	ds_read_b128 v[180:183], v133 offset:22528
	v_mfma_f32_16x16x32_bf16 v[44:47], v[96:99], v[92:95], v[44:47]
	v_mfma_f32_16x16x32_bf16 v[40:43], v[96:99], v[100:103], v[40:43]
	v_mfma_f32_16x16x32_bf16 v[36:39], v[96:99], v[108:111], v[36:39]
	v_mfma_f32_16x16x32_bf16 v[32:35], v[96:99], v[116:119], v[32:35]
	v_mfma_f32_16x16x32_bf16 v[28:31], v[104:107], v[92:95], v[28:31]
	v_mfma_f32_16x16x32_bf16 v[24:27], v[104:107], v[100:103], v[24:27]
	v_mfma_f32_16x16x32_bf16 v[20:23], v[104:107], v[108:111], v[20:23]
	v_mfma_f32_16x16x32_bf16 v[16:19], v[104:107], v[116:119], v[16:19]
	v_mfma_f32_16x16x32_bf16 v[12:15], v[112:115], v[92:95], v[12:15]
	v_mfma_f32_16x16x32_bf16 v[8:11], v[112:115], v[100:103], v[8:11]
	v_mfma_f32_16x16x32_bf16 v[4:7], v[112:115], v[108:111], v[4:7]
	v_mfma_f32_16x16x32_bf16 v[0:3], v[112:115], v[116:119], v[0:3]
	s_waitcnt vmcnt(0) lgkmcnt(0)
	s_barrier
	v_add_u32_e32 v128, s17, v82
	s_add_i32 s17, s18, 32
	v_add_u32_e32 v134, s17, v85
	v_add_u32_e32 v135, s17, v86
	v_add_u32_e32 v132, v134, v84
	v_add_u32_e32 v133, v135, v84
	ds_read_b128 v[88:91], v132
	ds_read_b128 v[96:99], v132 offset:2048
	ds_read_b128 v[104:107], v132 offset:4096
	ds_read_b128 v[112:115], v132 offset:6144
	ds_read_b128 v[92:95], v133 offset:16384
	ds_read_b128 v[100:103], v133 offset:18432
	ds_read_b128 v[108:111], v133 offset:20480
	ds_read_b128 v[116:119], v133 offset:22528
	v_readfirstlane_b32 s18, v128
	v_mfma_f32_16x16x32_bf16 v[60:63], v[152:155], v[168:171], v[60:63]
	v_lshl_add_u64 v[130:131], v[64:65], 0, s[42:43]
	s_mov_b32 m0, s18
	s_nop 0
	global_load_lds_dwordx4 v[130:131], off
	v_mfma_f32_16x16x32_bf16 v[56:59], v[152:155], v[172:175], v[56:59]
	v_mfma_f32_16x16x32_bf16 v[52:55], v[152:155], v[176:179], v[52:55]
	v_lshl_add_u64 v[130:131], v[72:73], 0, s[42:43]
	s_add_i32 m0, s18, 0x4000
	s_nop 0
	global_load_lds_dwordx4 v[130:131], off
	v_mfma_f32_16x16x32_bf16 v[48:51], v[152:155], v[180:183], v[48:51]
	v_mfma_f32_16x16x32_bf16 v[44:47], v[156:159], v[168:171], v[44:47]
	v_lshl_add_u64 v[130:131], v[66:67], 0, s[42:43]
	s_add_i32 m0, s18, 0x400
	s_nop 0
	global_load_lds_dwordx4 v[130:131], off
	v_mfma_f32_16x16x32_bf16 v[40:43], v[156:159], v[172:175], v[40:43]
	v_mfma_f32_16x16x32_bf16 v[36:39], v[156:159], v[176:179], v[36:39]
	v_lshl_add_u64 v[130:131], v[74:75], 0, s[42:43]
	s_add_i32 m0, s18, 0x4400
	s_nop 0
	global_load_lds_dwordx4 v[130:131], off
	v_mfma_f32_16x16x32_bf16 v[32:35], v[156:159], v[180:183], v[32:35]
	v_mfma_f32_16x16x32_bf16 v[28:31], v[160:163], v[168:171], v[28:31]
	v_lshl_add_u64 v[130:131], v[68:69], 0, s[42:43]
	s_add_i32 m0, s18, 0x800
	s_nop 0
	global_load_lds_dwordx4 v[130:131], off
	v_mfma_f32_16x16x32_bf16 v[24:27], v[160:163], v[172:175], v[24:27]
	v_mfma_f32_16x16x32_bf16 v[20:23], v[160:163], v[176:179], v[20:23]
	v_lshl_add_u64 v[130:131], v[76:77], 0, s[42:43]
	s_add_i32 m0, s18, 0x4800
	s_nop 0
	global_load_lds_dwordx4 v[130:131], off
	v_mfma_f32_16x16x32_bf16 v[16:19], v[160:163], v[180:183], v[16:19]
	v_mfma_f32_16x16x32_bf16 v[12:15], v[164:167], v[168:171], v[12:15]
	v_lshl_add_u64 v[130:131], v[70:71], 0, s[42:43]
	s_add_i32 m0, s18, 0xc00
	s_nop 0
	global_load_lds_dwordx4 v[130:131], off
	v_mfma_f32_16x16x32_bf16 v[8:11], v[164:167], v[172:175], v[8:11]
	v_mfma_f32_16x16x32_bf16 v[4:7], v[164:167], v[176:179], v[4:7]
	v_lshl_add_u64 v[130:131], v[78:79], 0, s[42:43]
	s_add_i32 m0, s18, 0x4c00
	s_nop 0
	global_load_lds_dwordx4 v[130:131], off
	v_mfma_f32_16x16x32_bf16 v[0:3], v[164:167], v[180:183], v[0:3]
	s_add_i32 s16, s16, 0x8000
	s_add_u32 s42, s42, 0x80
	s_addc_u32 s43, s43, 0
	s_cmpk_lg_i32 s42, 0x780
	s_cbranch_scc1 .Lg65_loop
	s_and_b32 s17, s16, 0x8000
	s_xor_b32 s18, s17, 0x8000
	v_add_u32_e32 v132, v134, v83
	v_add_u32_e32 v133, v135, v83
	ds_read_b128 v[152:155], v132
	ds_read_b128 v[156:159], v132 offset:2048
	ds_read_b128 v[160:163], v132 offset:4096
	ds_read_b128 v[164:167], v132 offset:6144
	s_waitcnt lgkmcnt(4)
	v_mfma_f32_16x16x32_bf16 v[60:63], v[88:91], v[92:95], v[60:63]
	v_mfma_f32_16x16x32_bf16 v[56:59], v[88:91], v[100:103], v[56:59]
	v_mfma_f32_16x16x32_bf16 v[52:55], v[88:91], v[108:111], v[52:55]
	v_mfma_f32_16x16x32_bf16 v[48:51], v[88:91], v[116:119], v[48:51]
	ds_read_b128 v[168:171], v133 offset:16384
	ds_read_b128 v[172:175], v133 offset:18432
	ds_read_b128 v[176:179], v133 offset:20480
	ds_read_b128 v[180:183], v133 offset:22528
	v_mfma_f32_16x16x32_bf16 v[44:47], v[96:99], v[92:95], v[44:47]
	v_mfma_f32_16x16x32_bf16 v[40:43], v[96:99], v[100:103], v[40:43]
	v_mfma_f32_16x16x32_bf16 v[36:39], v[96:99], v[108:111], v[36:39]
	v_mfma_f32_16x16x32_bf16 v[32:35], v[96:99], v[116:119], v[32:35]
	v_mfma_f32_16x16x32_bf16 v[28:31], v[104:107], v[92:95], v[28:31]
	v_mfma_f32_16x16x32_bf16 v[24:27], v[104:107], v[100:103], v[24:27]
	v_mfma_f32_16x16x32_bf16 v[20:23], v[104:107], v[108:111], v[20:23]
	v_mfma_f32_16x16x32_bf16 v[16:19], v[104:107], v[116:119], v[16:19]
	v_mfma_f32_16x16x32_bf16 v[12:15], v[112:115], v[92:95], v[12:15]
	v_mfma_f32_16x16x32_bf16 v[8:11], v[112:115], v[100:103], v[8:11]
	v_mfma_f32_16x16x32_bf16 v[4:7], v[112:115], v[108:111], v[4:7]
	v_mfma_f32_16x16x32_bf16 v[0:3], v[112:115], v[116:119], v[0:3]
	s_waitcnt vmcnt(0) lgkmcnt(0)
	s_barrier
	v_mfma_f32_16x16x32_bf16 v[60:63], v[152:155], v[168:171], v[60:63]
	v_mfma_f32_16x16x32_bf16 v[56:59], v[152:155], v[172:175], v[56:59]
	v_mfma_f32_16x16x32_bf16 v[52:55], v[152:155], v[176:179], v[52:55]
	v_mfma_f32_16x16x32_bf16 v[48:51], v[152:155], v[180:183], v[48:51]
	v_mfma_f32_16x16x32_bf16 v[44:47], v[156:159], v[168:171], v[44:47]
	v_mfma_f32_16x16x32_bf16 v[40:43], v[156:159], v[172:175], v[40:43]
	v_mfma_f32_16x16x32_bf16 v[36:39], v[156:159], v[176:179], v[36:39]
	v_mfma_f32_16x16x32_bf16 v[32:35], v[156:159], v[180:183], v[32:35]
	v_mfma_f32_16x16x32_bf16 v[28:31], v[160:163], v[168:171], v[28:31]
	v_mfma_f32_16x16x32_bf16 v[24:27], v[160:163], v[172:175], v[24:27]
	v_mfma_f32_16x16x32_bf16 v[20:23], v[160:163], v[176:179], v[20:23]
	v_mfma_f32_16x16x32_bf16 v[16:19], v[160:163], v[180:183], v[16:19]
	v_mfma_f32_16x16x32_bf16 v[12:15], v[164:167], v[168:171], v[12:15]
	v_mfma_f32_16x16x32_bf16 v[8:11], v[164:167], v[172:175], v[8:11]
	v_mfma_f32_16x16x32_bf16 v[4:7], v[164:167], v[176:179], v[4:7]
	v_mfma_f32_16x16x32_bf16 v[0:3], v[164:167], v[180:183], v[0:3]
	v_add_u32_e32 v100, 32, v85
	v_add_u32_e32 v96, v100, v84
	ds_read_b128 v[64:67], v96 offset:32768
	ds_read_b128 v[72:75], v96 offset:38912
	ds_read_b128 v[88:91], v96 offset:36864
	ds_read_b128 v[96:99], v96 offset:34816
	v_add_u32_e32 v82, 32, v86
	v_add_u32_e32 v92, v82, v84
	ds_read_b128 v[68:71], v92 offset:55296
	ds_read_b128 v[76:79], v92 offset:49152
	ds_read_b128 v[84:87], v92 offset:53248
	ds_read_b128 v[92:95], v92 offset:51200
	s_waitcnt lgkmcnt(0)
	v_mfma_f32_16x16x32_bf16 v[56:59], v[64:67], v[92:95], v[56:59]
	v_readlane_b32 s44, v252, 11
	v_readlane_b32 s45, v252, 12
	s_add_i32 s11, s11, s5
	v_mfma_f32_16x16x32_bf16 v[44:47], v[96:99], v[76:79], v[44:47]
	s_cmp_ge_u32 s11, s3
	v_readlane_b32 s46, v252, 13
	v_readlane_b32 s47, v252, 14
	v_mfma_f32_16x16x32_bf16 v[40:43], v[96:99], v[92:95], v[40:43]
	v_readlane_b32 s48, v252, 15
	v_readlane_b32 s49, v252, 16
	v_readlane_b32 s50, v252, 17
	v_mfma_f32_16x16x32_bf16 v[36:39], v[96:99], v[84:87], v[36:39]
	v_readlane_b32 s51, v252, 18
	v_mfma_f32_16x16x32_bf16 v[32:35], v[96:99], v[68:71], v[32:35]
	v_mfma_f32_16x16x32_bf16 v[96:99], v[88:91], v[92:95], v[24:27]
	v_mfma_f32_16x16x32_bf16 v[92:95], v[72:75], v[92:95], v[8:11]
	s_nop 2
	v_add_u32_e32 v8, v100, v83
	v_mfma_f32_16x16x32_bf16 v[60:63], v[64:67], v[76:79], v[60:63]
	v_add_u32_e32 v9, v82, v83
	v_mfma_f32_16x16x32_bf16 v[52:55], v[64:67], v[84:87], v[52:55]
	v_mfma_f32_16x16x32_bf16 v[48:51], v[64:67], v[68:71], v[48:51]
	v_mfma_f32_16x16x32_bf16 v[64:67], v[88:91], v[76:79], v[28:31]
	v_mfma_f32_16x16x32_bf16 v[20:23], v[88:91], v[84:87], v[20:23]
	v_mfma_f32_16x16x32_bf16 v[88:91], v[88:91], v[68:71], v[16:19]
	v_mfma_f32_16x16x32_bf16 v[76:79], v[72:75], v[76:79], v[12:15]
	v_mfma_f32_16x16x32_bf16 v[4:7], v[72:75], v[84:87], v[4:7]
	v_mfma_f32_16x16x32_bf16 v[68:71], v[72:75], v[68:71], v[0:3]
	ds_read_b128 v[72:75], v9 offset:49152
	ds_read_b128 v[12:15], v8 offset:34816
	ds_read_b128 v[100:103], v8 offset:36864
	ds_read_b128 v[0:3], v8 offset:32768
	ds_read_b128 v[108:111], v8 offset:38912
	ds_read_b128 v[104:107], v9 offset:53248
	ds_read_b128 v[112:115], v9 offset:55296
	ds_read_b128 v[82:85], v9 offset:51200
	s_waitcnt lgkmcnt(4)
	v_mfma_f32_16x16x32_bf16 v[60:63], v[0:3], v[72:75], v[60:63]
	s_waitcnt vmcnt(0)
	s_waitcnt lgkmcnt(0)
	s_barrier
	v_mfma_f32_16x16x32_bf16 v[24:27], v[0:3], v[104:107], v[52:55]
	v_mfma_f32_16x16x32_bf16 v[44:47], v[12:15], v[72:75], v[44:47]
	v_mfma_f32_16x16x32_bf16 v[28:31], v[12:15], v[104:107], v[36:39]
	v_mfma_f32_16x16x32_bf16 v[36:39], v[100:103], v[72:75], v[64:67]
	v_mfma_f32_16x16x32_bf16 v[16:19], v[100:103], v[104:107], v[20:23]
	v_mfma_f32_16x16x32_bf16 v[52:55], v[108:111], v[72:75], v[76:79]
	v_mul_f32_e32 v72, 0xbfb8aa3b, v61
	v_exp_f32_e32 v72, v72
	v_mul_f32_e32 v73, 0xbfb8aa3b, v63
	v_mfma_f32_16x16x32_bf16 v[20:23], v[108:111], v[104:107], v[4:7]
	v_exp_f32_e32 v73, v73
	s_nop 0
	v_add_f32_e32 v73, 1.0, v73
	v_mfma_f32_16x16x32_bf16 v[4:7], v[108:111], v[112:115], v[68:71]
	v_rcp_f32_e32 v73, v73
	s_nop 1
	v_mul_f32_e32 v71, 0xbfb8aa3b, v60
	v_exp_f32_e32 v71, v71
	v_lshrrev_b32_e32 v70, 1, v80
	v_and_b32_e32 v192, 24, v70
	v_mfma_f32_16x16x32_bf16 v[56:59], v[0:3], v[82:85], v[56:59]
	v_add_f32_e32 v70, 1.0, v71
	v_add_f32_e32 v71, 1.0, v72
	v_mul_f32_e32 v72, 0xbfb8aa3b, v62
	v_exp_f32_e32 v72, v72
	v_rcp_f32_e32 v70, v70
	v_rcp_f32_e32 v71, v71
	v_mfma_f32_16x16x32_bf16 v[40:43], v[12:15], v[82:85], v[40:43]
	v_add_f32_e32 v72, 1.0, v72
	v_rcp_f32_e32 v72, v72
	v_pk_mul_f32 v[60:61], v[60:61], v[70:71]
	v_mfma_f32_16x16x32_bf16 v[12:15], v[12:15], v[112:115], v[32:35]
	v_mul_f32_e64 v44, v44, v60
	v_mul_f32_e64 v45, v45, v61
	v_pk_mul_f32 v[60:61], v[62:63], v[72:73]
	v_cvt_pk_bf16_f32 v44, v44, v45
	v_mul_f32_e32 v45, 0xbfb8aa3b, v36
	v_pk_mul_f32 v[46:47], v[46:47], v[60:61]
	v_exp_f32_e32 v60, v45
	v_mul_f32_e32 v45, 0xbfb8aa3b, v37
	v_exp_f32_e32 v61, v45
	v_cvt_pk_bf16_f32 v45, v46, v47
	v_add_f32_e32 v46, 1.0, v60
	v_mul_f32_e32 v60, 0xbfb8aa3b, v38
	v_add_f32_e32 v47, 1.0, v61
	v_mul_f32_e32 v61, 0xbfb8aa3b, v39
	v_exp_f32_e32 v60, v60
	v_exp_f32_e32 v61, v61
	v_rcp_f32_e32 v46, v46
	v_rcp_f32_e32 v47, v47
	v_add_f32_e32 v60, 1.0, v60
	v_add_f32_e32 v61, 1.0, v61
	v_rcp_f32_e32 v60, v60
	v_rcp_f32_e32 v61, v61
	v_add_u32_e32 v32, s8, v81
	v_and_b32_e32 v33, 0x4f, v80
	v_ashrrev_i32_e32 v32, 1, v32
	v_or_b32_e32 v74, s12, v33
	v_ashrrev_i32_e32 v33, 31, v32
	v_mov_b64_e32 v[34:35], s[44:45]
	s_movk_i32 s8, 0x1600
	v_pk_mul_f32 v[36:37], v[36:37], v[46:47]
	v_pk_mul_f32 v[38:39], v[38:39], v[60:61]
	v_mad_i64_i32 v[68:69], s[16:17], v74, s8, v[34:35]
	v_lshlrev_b64 v[32:33], 1, v[32:33]
	v_pk_mul_f32 v[36:37], v[52:53], v[36:37]
	v_pk_mul_f32 v[38:39], v[54:55], v[38:39]
	v_lshl_add_u64 v[68:69], v[68:69], 0, v[32:33]
	v_cvt_pk_bf16_f32 v36, v36, v37
	v_cvt_pk_bf16_f32 v37, v38, v39
	v_mul_f32_e32 v38, 0xbfb8aa3b, v56
	v_mul_f32_e32 v39, 0xbfb8aa3b, v57
	v_lshl_add_u64 v[68:69], v[68:69], 0, v[192:193]
	v_exp_f32_e32 v38, v38
	v_exp_f32_e32 v39, v39
	global_store_dwordx2 v[68:69], v[44:45], off
	v_mul_f32_e32 v44, 0xbfb8aa3b, v58
	v_mul_f32_e32 v45, 0xbfb8aa3b, v59
	v_exp_f32_e32 v44, v44
	v_exp_f32_e32 v45, v45
	v_add_f32_e32 v38, 1.0, v38
	v_add_f32_e32 v39, 1.0, v39
	v_rcp_f32_e32 v38, v38
	v_rcp_f32_e32 v39, v39
	v_add_f32_e32 v44, 1.0, v44
	v_add_f32_e32 v45, 1.0, v45
	v_mfma_f32_16x16x32_bf16 v[8:11], v[0:3], v[112:115], v[48:51]
	v_rcp_f32_e32 v44, v44
	v_rcp_f32_e32 v45, v45
	v_pk_mul_f32 v[38:39], v[56:57], v[38:39]
	v_mfma_f32_16x16x32_bf16 v[48:51], v[100:103], v[82:85], v[96:99]
	v_mul_f32_e64 v38, v40, v38
	v_mul_f32_e64 v39, v41, v39
	v_pk_mul_f32 v[40:41], v[58:59], v[44:45]
	v_cvt_pk_bf16_f32 v38, v38, v39
	v_pk_mul_f32 v[40:41], v[42:43], v[40:41]
	global_store_dwordx2 v[68:69], v[36:37], off offset:32
	s_nop 1
	v_mul_f32_e32 v39, 0xbfb8aa3b, v48
	v_exp_f32_e32 v42, v39
	v_mul_f32_e32 v39, 0xbfb8aa3b, v49
	v_exp_f32_e32 v43, v39
	v_cvt_pk_bf16_f32 v39, v40, v41
	v_add_f32_e32 v40, 1.0, v42
	v_mul_f32_e32 v42, 0xbfb8aa3b, v50
	v_add_f32_e32 v41, 1.0, v43
	v_mul_f32_e32 v43, 0xbfb8aa3b, v51
	v_exp_f32_e32 v42, v42
	v_exp_f32_e32 v43, v43
	v_or_b32_e32 v36, 16, v74
	v_rcp_f32_e32 v40, v40
	v_add_f32_e32 v42, 1.0, v42
	v_add_f32_e32 v43, 1.0, v43
	v_rcp_f32_e32 v41, v41
	v_rcp_f32_e32 v42, v42
	v_rcp_f32_e32 v43, v43
	v_mfma_f32_16x16x32_bf16 v[64:67], v[108:111], v[82:85], v[92:95]
	v_mad_i64_i32 v[36:37], s[16:17], v36, s8, v[34:35]
	v_lshl_add_u64 v[36:37], v[36:37], 0, v[32:33]
	v_lshl_add_u64 v[36:37], v[36:37], 0, v[192:193]
	global_store_dwordx2 v[36:37], v[38:39], off
	v_pk_mul_f32 v[38:39], v[48:49], v[40:41]
	v_pk_mul_f32 v[40:41], v[50:51], v[42:43]
	s_nop 1
	v_pk_mul_f32 v[38:39], v[64:65], v[38:39]
	v_pk_mul_f32 v[40:41], v[66:67], v[40:41]
	v_cvt_pk_bf16_f32 v38, v38, v39
	v_cvt_pk_bf16_f32 v39, v40, v41
	global_store_dwordx2 v[36:37], v[38:39], off offset:32
	v_mul_f32_e32 v38, 0xbfb8aa3b, v24
	v_mul_f32_e32 v39, 0xbfb8aa3b, v25
	v_exp_f32_e32 v38, v38
	v_exp_f32_e32 v39, v39
	v_mul_f32_e32 v40, 0xbfb8aa3b, v26
	v_mul_f32_e32 v41, 0xbfb8aa3b, v27
	v_add_f32_e32 v38, 1.0, v38
	v_add_f32_e32 v39, 1.0, v39
	v_rcp_f32_e32 v38, v38
	v_rcp_f32_e32 v39, v39
	v_exp_f32_e32 v40, v40
	v_exp_f32_e32 v41, v41
	v_mfma_f32_16x16x32_bf16 v[0:3], v[100:103], v[112:115], v[88:91]
	v_mul_f32_e64 v24, v24, v38
	v_mul_f32_e64 v25, v25, v39
	v_add_f32_e32 v40, 1.0, v40
	v_add_f32_e32 v41, 1.0, v41
	v_pk_mul_f32 v[24:25], v[28:29], v[24:25]
	v_rcp_f32_e32 v40, v40
	v_rcp_f32_e32 v41, v41
	v_cvt_pk_bf16_f32 v24, v24, v25
	v_mul_f32_e32 v25, 0xbfb8aa3b, v16
	v_exp_f32_e32 v28, v25
	v_mul_f32_e32 v25, 0xbfb8aa3b, v17
	v_exp_f32_e32 v29, v25
	v_pk_mul_f32 v[26:27], v[26:27], v[40:41]
	v_or_b32_e32 v36, 32, v74
	v_pk_mul_f32 v[26:27], v[30:31], v[26:27]
	v_mad_i64_i32 v[36:37], s[16:17], v36, s8, v[34:35]
	v_cvt_pk_bf16_f32 v25, v26, v27
	v_add_f32_e32 v26, 1.0, v28
	v_add_f32_e32 v27, 1.0, v29
	v_mul_f32_e32 v28, 0xbfb8aa3b, v18
	v_mul_f32_e32 v29, 0xbfb8aa3b, v19
	v_exp_f32_e32 v28, v28
	v_exp_f32_e32 v29, v29
	v_rcp_f32_e32 v26, v26
	v_rcp_f32_e32 v27, v27
	v_add_f32_e32 v28, 1.0, v28
	v_add_f32_e32 v29, 1.0, v29
	v_rcp_f32_e32 v28, v28
	v_rcp_f32_e32 v29, v29
	v_pk_mul_f32 v[16:17], v[16:17], v[26:27]
	v_lshl_add_u64 v[36:37], v[36:37], 0, v[32:33]
	v_pk_mul_f32 v[16:17], v[20:21], v[16:17]
	v_pk_mul_f32 v[18:19], v[18:19], v[28:29]
	v_cvt_pk_bf16_f32 v16, v16, v17
	v_pk_mul_f32 v[18:19], v[22:23], v[18:19]
	v_mul_f32_e32 v20, 0xbfb8aa3b, v10
	v_cvt_pk_bf16_f32 v17, v18, v19
	v_mul_f32_e32 v18, 0xbfb8aa3b, v8
	v_mul_f32_e32 v19, 0xbfb8aa3b, v9
	v_exp_f32_e32 v18, v18
	v_exp_f32_e32 v19, v19
	v_mul_f32_e32 v21, 0xbfb8aa3b, v11
	v_exp_f32_e32 v20, v20
	v_add_f32_e32 v18, 1.0, v18
	v_add_f32_e32 v19, 1.0, v19
	v_rcp_f32_e32 v18, v18
	v_rcp_f32_e32 v19, v19
	v_exp_f32_e32 v21, v21
	v_add_f32_e32 v20, 1.0, v20
	v_rcp_f32_e32 v20, v20
	v_pk_mul_f32 v[8:9], v[8:9], v[18:19]
	v_add_f32_e32 v21, 1.0, v21
	v_pk_mul_f32 v[8:9], v[12:13], v[8:9]
	v_rcp_f32_e32 v21, v21
	v_cvt_pk_bf16_f32 v8, v8, v9
	v_mul_f32_e32 v9, 0xbfb8aa3b, v0
	v_exp_f32_e32 v12, v9
	v_mul_f32_e32 v9, 0xbfb8aa3b, v1
	v_exp_f32_e32 v13, v9
	v_pk_mul_f32 v[10:11], v[10:11], v[20:21]
	v_lshl_add_u64 v[36:37], v[36:37], 0, v[192:193]
	v_pk_mul_f32 v[10:11], v[14:15], v[10:11]
	global_store_dwordx2 v[36:37], v[16:17], off offset:32
	v_cvt_pk_bf16_f32 v9, v10, v11
	v_add_f32_e32 v10, 1.0, v12
	v_add_f32_e32 v11, 1.0, v13
	v_mul_f32_e32 v12, 0xbfb8aa3b, v2
	v_mul_f32_e32 v13, 0xbfb8aa3b, v3
	v_exp_f32_e32 v12, v12
	v_exp_f32_e32 v13, v13
	v_rcp_f32_e32 v10, v10
	v_rcp_f32_e32 v11, v11
	v_add_f32_e32 v12, 1.0, v12
	v_add_f32_e32 v13, 1.0, v13
	v_rcp_f32_e32 v12, v12
	v_rcp_f32_e32 v13, v13
	v_or_b32_e32 v16, 48, v74
	v_mad_i64_i32 v[16:17], s[16:17], v16, s8, v[34:35]
	v_pk_mul_f32 v[0:1], v[0:1], v[10:11]
	v_pk_mul_f32 v[2:3], v[2:3], v[12:13]
	v_lshl_add_u64 v[16:17], v[16:17], 0, v[32:33]
	v_pk_mul_f32 v[0:1], v[4:5], v[0:1]
	v_pk_mul_f32 v[2:3], v[6:7], v[2:3]
	v_lshl_add_u64 v[16:17], v[16:17], 0, v[192:193]
	v_cvt_pk_bf16_f32 v0, v0, v1
	v_cvt_pk_bf16_f32 v1, v2, v3
	global_store_dwordx2 v[36:37], v[24:25], off
	global_store_dwordx2 v[16:17], v[8:9], off
	global_store_dwordx2 v[16:17], v[0:1], off offset:32
	s_cbranch_scc0 .LBB0_62

.LBB0_79:
	s_nop 1
	v_sub_co_u32_e64 v0, s[10:11], s2, 64
	s_and_b64 s[10:11], s[10:11], exec
	v_readfirstlane_b32 s3, v0
	v_mov_b32_e32 v80, v220
	s_cselect_b32 s3, s2, s3
	s_cselect_b32 s10, 0, 8
	v_ashrrev_i32_e32 v16, 6, v80
	v_bfe_u32 v19, v80, 4, 2
	s_bfe_u32 s12, s3, 0x50003
	v_bfe_u32 v17, v80, 3, 3
	v_lshlrev_b32_e32 v18, 5, v16
	v_xor_b32_e32 v0, v19, v80
	s_add_i32 s16, s3, s10
	s_lshl_b32 s3, s12, 7
	v_or_b32_e32 v1, v18, v17
	v_lshlrev_b32_e32 v0, 3, v0
	v_add_u32_e32 v2, s3, v1
	v_and_b32_e32 v20, 56, v0
	v_or_b32_e32 v3, 8, v1
	s_lshl_b32 s17, s12, 13
	s_lshl_b32 s18, s16, 10
	v_lshl_or_b32 v192, v2, 10, v20
	v_lshrrev_b32_e32 v2, 1, v3
	s_sub_i32 s10, s18, s17
	v_xor_b32_e32 v2, v2, v80
	s_or_b32 s10, s10, s31
	v_lshlrev_b32_e32 v2, 3, v2
	v_add_u32_e32 v4, s3, v3
	v_and_b32_e32 v21, 56, v2
	v_add_u32_e32 v3, s10, v3
	v_lshl_or_b32 v2, v4, 10, v21
	v_lshl_or_b32 v4, v3, 10, v21
	v_or_b32_e32 v3, 16, v1
	v_add_u32_e32 v0, s10, v1
	v_add_u32_e32 v5, s3, v3
	v_add_u32_e32 v3, s10, v3
	v_or_b32_e32 v1, 24, v1
	v_lshl_or_b32 v8, v3, 10, v20
	v_lshrrev_b32_e32 v3, 1, v1
	v_xor_b32_e32 v3, v3, v80
	v_lshlrev_b32_e32 v3, 3, v3
	s_cmp_lg_u32 32, -1
	v_lshl_or_b32 v6, v5, 10, v20
	v_add_u32_e32 v5, s3, v1
	v_and_b32_e32 v22, 56, v3
	v_add_u32_e32 v1, s10, v1
	v_lshlrev_b32_e32 v23, 12, v16
	s_cselect_b32 s19, 32, 0
	v_ashrrev_i32_e32 v3, 1, v80
	v_lshl_or_b32 v12, v1, 10, v22
	v_add_u32_e32 v82, s19, v23
	v_and_b32_e32 v1, 15, v80
	v_and_b32_e32 v81, 0xffffffc0, v3
	s_add_i32 s40, s19, 0x4000
	v_or_b32_e32 v24, v81, v1
	v_lshlrev_b32_e32 v1, 7, v80
	v_add_u32_e32 v3, s40, v23
	v_readfirstlane_b32 s40, v82
	v_lshl_or_b32 v0, v0, 10, v20
	v_and_b32_e32 v83, 0x2780, v1
	v_lshl_add_u64 v[14:15], v[192:193], 1, s[0:1]
	s_mov_b32 m0, s40
	v_mov_b32_e32 v1, v193
	v_readfirstlane_b32 s40, v3
	global_load_lds_dwordx4 v[14:15], off
	v_lshl_add_u64 v[0:1], v[0:1], 1, s[74:75]
	s_mov_b32 m0, s40
	v_mov_b32_e32 v3, v193
	s_add_i32 s40, s19, 0x400
	global_load_lds_dwordx4 v[0:1], off
	v_lshl_add_u64 v[0:1], v[2:3], 1, s[0:1]
	v_add_u32_e32 v2, s40, v23
	v_lshl_or_b32 v10, v5, 10, v22
	v_readfirstlane_b32 s40, v2
	s_mov_b32 m0, s40
	s_add_i32 s40, s19, 0x4400
	v_add_u32_e32 v2, s40, v23
	global_load_lds_dwordx4 v[0:1], off
	v_readfirstlane_b32 s40, v2
	s_mov_b32 m0, s40
	s_add_i32 s40, s19, 0x800
	v_mov_b32_e32 v5, v193
	v_add_u32_e32 v2, s40, v23
	v_lshl_add_u64 v[0:1], v[4:5], 1, s[74:75]
	v_readfirstlane_b32 s40, v2
	global_load_lds_dwordx4 v[0:1], off
	s_mov_b32 m0, s40
	s_add_i32 s40, s19, 0x4800
	v_mov_b32_e32 v7, v193
	v_add_u32_e32 v2, s40, v23
	v_lshl_add_u64 v[0:1], v[6:7], 1, s[0:1]
	v_readfirstlane_b32 s40, v2
	global_load_lds_dwordx4 v[0:1], off
	s_mov_b32 m0, s40
	s_add_i32 s40, s19, 0xc00
	v_mov_b32_e32 v9, v193
	v_add_u32_e32 v2, s40, v23
	s_addk_i32 s19, 0x4c00
	v_lshl_add_u64 v[0:1], v[8:9], 1, s[74:75]
	v_mov_b32_e32 v11, v193
	v_readfirstlane_b32 s40, v2
	v_add_u32_e32 v2, s19, v23
	global_load_lds_dwordx4 v[0:1], off
	v_lshl_add_u64 v[0:1], v[10:11], 1, s[0:1]
	s_mov_b32 m0, s40
	v_mov_b32_e32 v13, v193
	v_readfirstlane_b32 s19, v2
	global_load_lds_dwordx4 v[0:1], off
	v_lshl_add_u64 v[0:1], v[12:13], 1, s[74:75]
	s_mov_b32 m0, s19
	s_or_b32 s18, s18, s31
	global_load_lds_dwordx4 v[0:1], off
	v_bfe_u32 v0, v80, 1, 3
	v_xor_b32_e32 v1, v19, v0
	v_bitop3_b32 v0, v19, v0, 4 bitop3:0x36
	v_lshlrev_b32_e32 v84, 4, v0
	v_or_b32_e32 v0, s3, v17
	v_add_u32_e32 v0, v0, v18
	v_lshl_or_b32 v192, v0, 10, v20
	v_lshlrev_b32_e32 v0, 15, v16
	v_lshlrev_b32_e32 v86, 4, v1
	v_lshlrev_b32_e32 v1, 10, v17
	v_lshl_add_u32 v2, s12, 17, v0
	v_or_b32_e32 v2, v2, v1
	v_lshl_add_u64 v[64:65], v[192:193], 1, s[28:29]
	v_or3_b32 v192, v2, v21, s33
	v_lshl_add_u64 v[66:67], v[192:193], 1, s[28:29]
	v_or3_b32 v192, v2, v20, s68
	v_lshl_add_u64 v[68:69], v[192:193], 1, s[28:29]
	v_or3_b32 v192, v2, v22, s67
	v_add3_u32 v2, s18, v17, v18
	s_lshl_b32 s16, s16, 20
	v_subrev_u32_e32 v2, s17, v2
	s_or_b32 s17, s58, s16
	v_lshl_add_u64 v[70:71], v[192:193], 1, s[28:29]
	v_lshl_or_b32 v192, v2, 10, v20
	v_add_u32_e32 v2, s17, v0
	v_add3_u32 v2, v2, v1, v21
	s_lshl_b32 s12, s12, 23
	s_or_b32 s17, s59, s16
	v_readlane_b32 s9, v254, 34
	v_lshl_add_u64 v[72:73], v[192:193], 1, s[56:57]
	v_subrev_u32_e32 v192, s12, v2
	v_add_u32_e32 v2, s17, v0
	s_or_b32 s16, s9, s16
	v_add3_u32 v2, v2, v1, v20
	v_add_u32_e32 v0, s16, v0
	s_waitcnt vmcnt(0)
	v_lshl_add_u64 v[74:75], v[192:193], 1, s[56:57]
	v_subrev_u32_e32 v192, s12, v2
	v_add3_u32 v0, v0, v1, v22
	v_lshl_add_u64 v[76:77], v[192:193], 1, s[56:57]
	v_subrev_u32_e32 v192, s12, v0
	v_mov_b32_e32 v0, 0
	s_mov_b32 s11, 0
	v_lshlrev_b32_e32 v85, 7, v24
	v_lshl_add_u64 v[78:79], v[192:193], 1, s[56:57]
	s_mov_b64 s[40:41], 0
	v_mov_b32_e32 v1, v0
	v_mov_b32_e32 v2, v0
	v_mov_b32_e32 v3, v0
	v_mov_b32_e32 v4, v0
	v_mov_b32_e32 v5, v0
	v_mov_b32_e32 v6, v0
	v_mov_b32_e32 v7, v0
	v_mov_b32_e32 v8, v0
	v_mov_b32_e32 v9, v0
	v_mov_b32_e32 v10, v0
	v_mov_b32_e32 v11, v0
	v_mov_b32_e32 v12, v0
	v_mov_b32_e32 v13, v0
	v_mov_b32_e32 v14, v0
	v_mov_b32_e32 v15, v0
	v_mov_b32_e32 v16, v0
	v_mov_b32_e32 v17, v0
	v_mov_b32_e32 v18, v0
	v_mov_b32_e32 v19, v0
	v_mov_b32_e32 v20, v0
	v_mov_b32_e32 v21, v0
	v_mov_b32_e32 v22, v0
	v_mov_b32_e32 v23, v0
	v_mov_b32_e32 v24, v0
	v_mov_b32_e32 v25, v0
	v_mov_b32_e32 v26, v0
	v_mov_b32_e32 v27, v0
	v_mov_b32_e32 v28, v0
	v_mov_b32_e32 v29, v0
	v_mov_b32_e32 v30, v0
	v_mov_b32_e32 v31, v0
	v_mov_b32_e32 v32, v0
	v_mov_b32_e32 v33, v0
	v_mov_b32_e32 v34, v0
	v_mov_b32_e32 v35, v0
	v_mov_b32_e32 v36, v0
	v_mov_b32_e32 v37, v0
	v_mov_b32_e32 v38, v0
	v_mov_b32_e32 v39, v0
	v_mov_b32_e32 v40, v0
	v_mov_b32_e32 v41, v0
	v_mov_b32_e32 v42, v0
	v_mov_b32_e32 v43, v0
	v_mov_b32_e32 v44, v0
	v_mov_b32_e32 v45, v0
	v_mov_b32_e32 v46, v0
	v_mov_b32_e32 v47, v0
	v_mov_b32_e32 v48, v0
	v_mov_b32_e32 v49, v0
	v_mov_b32_e32 v50, v0
	v_mov_b32_e32 v51, v0
	v_mov_b32_e32 v52, v0
	v_mov_b32_e32 v53, v0
	v_mov_b32_e32 v54, v0
	v_mov_b32_e32 v55, v0
	v_mov_b32_e32 v56, v0
	v_mov_b32_e32 v57, v0
	v_mov_b32_e32 v58, v0
	v_mov_b32_e32 v59, v0
	v_mov_b32_e32 v60, v0
	v_mov_b32_e32 v61, v0
	v_mov_b32_e32 v62, v0
	v_mov_b32_e32 v63, v0
	s_waitcnt vmcnt(0) lgkmcnt(0)
	s_barrier
	v_add_u32_e32 v134, 32, v85
	v_add_u32_e32 v135, 32, v83
	v_add_u32_e32 v132, v134, v86
	v_add_u32_e32 v133, v135, v86
	ds_read_b128 v[88:91], v132
	ds_read_b128 v[96:99], v132 offset:2048
	ds_read_b128 v[104:107], v132 offset:4096
	ds_read_b128 v[112:115], v132 offset:6144
	ds_read_b128 v[92:95], v133 offset:16384
	ds_read_b128 v[100:103], v133 offset:18432
	ds_read_b128 v[108:111], v133 offset:20480
	ds_read_b128 v[116:119], v133 offset:22528
	v_add_u32_e32 v128, 0x8000, v82
	s_nop 0
	v_readfirstlane_b32 s16, v128
	s_nop 1
	v_lshl_add_u64 v[130:131], v[64:65], 0, s[40:41]
	s_mov_b32 m0, s16
	s_nop 0
	global_load_lds_dwordx4 v[130:131], off
	v_lshl_add_u64 v[130:131], v[72:73], 0, s[40:41]
	s_add_i32 m0, s16, 0x4000
	s_nop 0
	global_load_lds_dwordx4 v[130:131], off
	v_lshl_add_u64 v[130:131], v[66:67], 0, s[40:41]
	s_add_i32 m0, s16, 0x400
	s_nop 0
	global_load_lds_dwordx4 v[130:131], off
	v_lshl_add_u64 v[130:131], v[74:75], 0, s[40:41]
	s_add_i32 m0, s16, 0x4400
	s_nop 0
	global_load_lds_dwordx4 v[130:131], off
	v_lshl_add_u64 v[130:131], v[68:69], 0, s[40:41]
	s_add_i32 m0, s16, 0x800
	s_nop 0
	global_load_lds_dwordx4 v[130:131], off
	v_lshl_add_u64 v[130:131], v[76:77], 0, s[40:41]
	s_add_i32 m0, s16, 0x4800
	s_nop 0
	global_load_lds_dwordx4 v[130:131], off
	v_lshl_add_u64 v[130:131], v[70:71], 0, s[40:41]
	s_add_i32 m0, s16, 0xc00
	s_nop 0
	global_load_lds_dwordx4 v[130:131], off
	v_lshl_add_u64 v[130:131], v[78:79], 0, s[40:41]
	s_add_i32 m0, s16, 0x4c00
	s_nop 0
	global_load_lds_dwordx4 v[130:131], off
	s_add_u32 s40, s40, 0x80
	s_addc_u32 s41, s41, 0
.Lg80_loop:
	s_and_b32 s12, s11, 0x8000
	s_xor_b32 s16, s12, 0x8000
	v_add_u32_e32 v132, v134, v84
	v_add_u32_e32 v133, v135, v84
	ds_read_b128 v[152:155], v132
	ds_read_b128 v[156:159], v132 offset:2048
	ds_read_b128 v[160:163], v132 offset:4096
	ds_read_b128 v[164:167], v132 offset:6144
	s_waitcnt lgkmcnt(4)
	v_mfma_f32_16x16x32_bf16 v[60:63], v[88:91], v[92:95], v[60:63]
	v_mfma_f32_16x16x32_bf16 v[56:59], v[88:91], v[100:103], v[56:59]
	v_mfma_f32_16x16x32_bf16 v[52:55], v[88:91], v[108:111], v[52:55]
	v_mfma_f32_16x16x32_bf16 v[48:51], v[88:91], v[116:119], v[48:51]
	ds_read_b128 v[168:171], v133 offset:16384
	ds_read_b128 v[172:175], v133 offset:18432
	ds_read_b128 v[176:179], v133 offset:20480
	ds_read_b128 v[180:183], v133 offset:22528
	v_mfma_f32_16x16x32_bf16 v[44:47], v[96:99], v[92:95], v[44:47]
	v_mfma_f32_16x16x32_bf16 v[40:43], v[96:99], v[100:103], v[40:43]
	v_mfma_f32_16x16x32_bf16 v[36:39], v[96:99], v[108:111], v[36:39]
	v_mfma_f32_16x16x32_bf16 v[32:35], v[96:99], v[116:119], v[32:35]
	v_mfma_f32_16x16x32_bf16 v[28:31], v[104:107], v[92:95], v[28:31]
	v_mfma_f32_16x16x32_bf16 v[24:27], v[104:107], v[100:103], v[24:27]
	v_mfma_f32_16x16x32_bf16 v[20:23], v[104:107], v[108:111], v[20:23]
	v_mfma_f32_16x16x32_bf16 v[16:19], v[104:107], v[116:119], v[16:19]
	v_mfma_f32_16x16x32_bf16 v[12:15], v[112:115], v[92:95], v[12:15]
	v_mfma_f32_16x16x32_bf16 v[8:11], v[112:115], v[100:103], v[8:11]
	v_mfma_f32_16x16x32_bf16 v[4:7], v[112:115], v[108:111], v[4:7]
	v_mfma_f32_16x16x32_bf16 v[0:3], v[112:115], v[116:119], v[0:3]
	s_waitcnt vmcnt(0) lgkmcnt(0)
	s_barrier
	v_add_u32_e32 v128, s12, v82
	s_add_i32 s12, s16, 32
	v_add_u32_e32 v134, s12, v85
	v_add_u32_e32 v135, s12, v83
	v_add_u32_e32 v132, v134, v86
	v_add_u32_e32 v133, v135, v86
	ds_read_b128 v[88:91], v132
	ds_read_b128 v[96:99], v132 offset:2048
	ds_read_b128 v[104:107], v132 offset:4096
	ds_read_b128 v[112:115], v132 offset:6144
	ds_read_b128 v[92:95], v133 offset:16384
	ds_read_b128 v[100:103], v133 offset:18432
	ds_read_b128 v[108:111], v133 offset:20480
	ds_read_b128 v[116:119], v133 offset:22528
	v_readfirstlane_b32 s16, v128
	v_mfma_f32_16x16x32_bf16 v[60:63], v[152:155], v[168:171], v[60:63]
	v_lshl_add_u64 v[130:131], v[64:65], 0, s[40:41]
	s_mov_b32 m0, s16
	s_nop 0
	global_load_lds_dwordx4 v[130:131], off
	v_mfma_f32_16x16x32_bf16 v[56:59], v[152:155], v[172:175], v[56:59]
	v_mfma_f32_16x16x32_bf16 v[52:55], v[152:155], v[176:179], v[52:55]
	v_lshl_add_u64 v[130:131], v[72:73], 0, s[40:41]
	s_add_i32 m0, s16, 0x4000
	s_nop 0
	global_load_lds_dwordx4 v[130:131], off
	v_mfma_f32_16x16x32_bf16 v[48:51], v[152:155], v[180:183], v[48:51]
	v_mfma_f32_16x16x32_bf16 v[44:47], v[156:159], v[168:171], v[44:47]
	v_lshl_add_u64 v[130:131], v[66:67], 0, s[40:41]
	s_add_i32 m0, s16, 0x400
	s_nop 0
	global_load_lds_dwordx4 v[130:131], off
	v_mfma_f32_16x16x32_bf16 v[40:43], v[156:159], v[172:175], v[40:43]
	v_mfma_f32_16x16x32_bf16 v[36:39], v[156:159], v[176:179], v[36:39]
	v_lshl_add_u64 v[130:131], v[74:75], 0, s[40:41]
	s_add_i32 m0, s16, 0x4400
	s_nop 0
	global_load_lds_dwordx4 v[130:131], off
	v_mfma_f32_16x16x32_bf16 v[32:35], v[156:159], v[180:183], v[32:35]
	v_mfma_f32_16x16x32_bf16 v[28:31], v[160:163], v[168:171], v[28:31]
	v_lshl_add_u64 v[130:131], v[68:69], 0, s[40:41]
	s_add_i32 m0, s16, 0x800
	s_nop 0
	global_load_lds_dwordx4 v[130:131], off
	v_mfma_f32_16x16x32_bf16 v[24:27], v[160:163], v[172:175], v[24:27]
	v_mfma_f32_16x16x32_bf16 v[20:23], v[160:163], v[176:179], v[20:23]
	v_lshl_add_u64 v[130:131], v[76:77], 0, s[40:41]
	s_add_i32 m0, s16, 0x4800
	s_nop 0
	global_load_lds_dwordx4 v[130:131], off
	v_mfma_f32_16x16x32_bf16 v[16:19], v[160:163], v[180:183], v[16:19]
	v_mfma_f32_16x16x32_bf16 v[12:15], v[164:167], v[168:171], v[12:15]
	v_lshl_add_u64 v[130:131], v[70:71], 0, s[40:41]
	s_add_i32 m0, s16, 0xc00
	s_nop 0
	global_load_lds_dwordx4 v[130:131], off
	v_mfma_f32_16x16x32_bf16 v[8:11], v[164:167], v[172:175], v[8:11]
	v_mfma_f32_16x16x32_bf16 v[4:7], v[164:167], v[176:179], v[4:7]
	v_lshl_add_u64 v[130:131], v[78:79], 0, s[40:41]
	s_add_i32 m0, s16, 0x4c00
	s_nop 0
	global_load_lds_dwordx4 v[130:131], off
	v_mfma_f32_16x16x32_bf16 v[0:3], v[164:167], v[180:183], v[0:3]
	s_add_i32 s11, s11, 0x8000
	s_add_u32 s40, s40, 0x80
	s_addc_u32 s41, s41, 0
	s_cmpk_lg_i32 s40, 0x780
	s_cbranch_scc1 .Lg80_loop
	s_and_b32 s12, s11, 0x8000
	s_xor_b32 s16, s12, 0x8000
	v_add_u32_e32 v132, v134, v84
	v_add_u32_e32 v133, v135, v84
	ds_read_b128 v[152:155], v132
	ds_read_b128 v[156:159], v132 offset:2048
	ds_read_b128 v[160:163], v132 offset:4096
	ds_read_b128 v[164:167], v132 offset:6144
	s_waitcnt lgkmcnt(4)
	v_mfma_f32_16x16x32_bf16 v[60:63], v[88:91], v[92:95], v[60:63]
	v_mfma_f32_16x16x32_bf16 v[56:59], v[88:91], v[100:103], v[56:59]
	v_mfma_f32_16x16x32_bf16 v[52:55], v[88:91], v[108:111], v[52:55]
	v_mfma_f32_16x16x32_bf16 v[48:51], v[88:91], v[116:119], v[48:51]
	ds_read_b128 v[168:171], v133 offset:16384
	ds_read_b128 v[172:175], v133 offset:18432
	ds_read_b128 v[176:179], v133 offset:20480
	ds_read_b128 v[180:183], v133 offset:22528
	v_mfma_f32_16x16x32_bf16 v[44:47], v[96:99], v[92:95], v[44:47]
	v_mfma_f32_16x16x32_bf16 v[40:43], v[96:99], v[100:103], v[40:43]
	v_mfma_f32_16x16x32_bf16 v[36:39], v[96:99], v[108:111], v[36:39]
	v_mfma_f32_16x16x32_bf16 v[32:35], v[96:99], v[116:119], v[32:35]
	v_mfma_f32_16x16x32_bf16 v[28:31], v[104:107], v[92:95], v[28:31]
	v_mfma_f32_16x16x32_bf16 v[24:27], v[104:107], v[100:103], v[24:27]
	v_mfma_f32_16x16x32_bf16 v[20:23], v[104:107], v[108:111], v[20:23]
	v_mfma_f32_16x16x32_bf16 v[16:19], v[104:107], v[116:119], v[16:19]
	v_mfma_f32_16x16x32_bf16 v[12:15], v[112:115], v[92:95], v[12:15]
	v_mfma_f32_16x16x32_bf16 v[8:11], v[112:115], v[100:103], v[8:11]
	v_mfma_f32_16x16x32_bf16 v[4:7], v[112:115], v[108:111], v[4:7]
	v_mfma_f32_16x16x32_bf16 v[0:3], v[112:115], v[116:119], v[0:3]
	s_waitcnt vmcnt(0) lgkmcnt(0)
	s_barrier
	v_mfma_f32_16x16x32_bf16 v[60:63], v[152:155], v[168:171], v[60:63]
	v_mfma_f32_16x16x32_bf16 v[56:59], v[152:155], v[172:175], v[56:59]
	v_mfma_f32_16x16x32_bf16 v[52:55], v[152:155], v[176:179], v[52:55]
	v_mfma_f32_16x16x32_bf16 v[48:51], v[152:155], v[180:183], v[48:51]
	v_mfma_f32_16x16x32_bf16 v[44:47], v[156:159], v[168:171], v[44:47]
	v_mfma_f32_16x16x32_bf16 v[40:43], v[156:159], v[172:175], v[40:43]
	v_mfma_f32_16x16x32_bf16 v[36:39], v[156:159], v[176:179], v[36:39]
	v_mfma_f32_16x16x32_bf16 v[32:35], v[156:159], v[180:183], v[32:35]
	v_mfma_f32_16x16x32_bf16 v[28:31], v[160:163], v[168:171], v[28:31]
	v_mfma_f32_16x16x32_bf16 v[24:27], v[160:163], v[172:175], v[24:27]
	v_mfma_f32_16x16x32_bf16 v[20:23], v[160:163], v[176:179], v[20:23]
	v_mfma_f32_16x16x32_bf16 v[16:19], v[160:163], v[180:183], v[16:19]
	v_mfma_f32_16x16x32_bf16 v[12:15], v[164:167], v[168:171], v[12:15]
	v_mfma_f32_16x16x32_bf16 v[8:11], v[164:167], v[172:175], v[8:11]
	v_mfma_f32_16x16x32_bf16 v[4:7], v[164:167], v[176:179], v[4:7]
	v_mfma_f32_16x16x32_bf16 v[0:3], v[164:167], v[180:183], v[0:3]
	v_add_u32_e32 v82, 32, v85
	v_add_u32_e32 v83, 32, v83
	v_add_u32_e32 v85, v82, v86
	ds_read_b128 v[64:67], v85 offset:32768
	v_add_u32_e32 v98, v83, v86
	ds_read_b128 v[72:75], v85 offset:34816
	ds_read_b128 v[86:89], v85 offset:36864
	ds_read_b128 v[94:97], v85 offset:38912
	ds_read_b128 v[90:93], v98 offset:53248
	ds_read_b128 v[68:71], v98 offset:49152
	ds_read_b128 v[76:79], v98 offset:51200
	ds_read_b128 v[98:101], v98 offset:55296
	s_waitcnt lgkmcnt(3)
	v_mfma_f32_16x16x32_bf16 v[52:55], v[64:67], v[90:93], v[52:55]
	s_add_i32 s2, s2, s8
	s_cmpk_gt_u32 s2, 0x7f
	v_mfma_f32_16x16x32_bf16 v[36:39], v[72:75], v[90:93], v[36:39]
	v_mfma_f32_16x16x32_bf16 v[20:23], v[86:89], v[90:93], v[20:23]
	v_mfma_f32_16x16x32_bf16 v[4:7], v[94:97], v[90:93], v[4:7]
	v_add_u32_e32 v90, v82, v84
	s_waitcnt lgkmcnt(2)
	v_mfma_f32_16x16x32_bf16 v[60:63], v[64:67], v[68:71], v[60:63]
	s_waitcnt lgkmcnt(1)
	v_mfma_f32_16x16x32_bf16 v[56:59], v[64:67], v[76:79], v[56:59]
	s_waitcnt lgkmcnt(0)
	v_mfma_f32_16x16x32_bf16 v[48:51], v[64:67], v[98:101], v[48:51]
	v_mfma_f32_16x16x32_bf16 v[44:47], v[72:75], v[68:71], v[44:47]
	v_mfma_f32_16x16x32_bf16 v[40:43], v[72:75], v[76:79], v[40:43]
	v_mfma_f32_16x16x32_bf16 v[32:35], v[72:75], v[98:101], v[32:35]
	v_mfma_f32_16x16x32_bf16 v[28:31], v[86:89], v[68:71], v[28:31]
	v_mfma_f32_16x16x32_bf16 v[24:27], v[86:89], v[76:79], v[24:27]
	v_mfma_f32_16x16x32_bf16 v[16:19], v[86:89], v[98:101], v[16:19]
	v_mfma_f32_16x16x32_bf16 v[12:15], v[94:97], v[68:71], v[12:15]
	v_mfma_f32_16x16x32_bf16 v[8:11], v[94:97], v[76:79], v[8:11]
	v_mfma_f32_16x16x32_bf16 v[0:3], v[94:97], v[98:101], v[0:3]
	ds_read_b128 v[64:67], v90 offset:32768
	v_add_u32_e32 v94, v83, v84
	ds_read_b128 v[72:75], v90 offset:34816
	ds_read_b128 v[82:85], v90 offset:36864
	ds_read_b128 v[90:93], v90 offset:38912
	ds_read_b128 v[68:71], v94 offset:49152
	ds_read_b128 v[76:79], v94 offset:51200
	ds_read_b128 v[86:89], v94 offset:53248
	ds_read_b128 v[94:97], v94 offset:55296
	s_waitcnt lgkmcnt(3)
	v_mfma_f32_16x16x32_bf16 v[60:63], v[64:67], v[68:71], v[60:63]
	s_waitcnt vmcnt(0)
	s_waitcnt lgkmcnt(0)
	s_barrier
	v_mfma_f32_16x16x32_bf16 v[56:59], v[64:67], v[76:79], v[56:59]
	s_nop 4
	v_cvt_pk_bf16_f32 v60, v60, v61
	v_cvt_pk_bf16_f32 v61, v62, v63
	v_mfma_f32_16x16x32_bf16 v[52:55], v[64:67], v[86:89], v[52:55]
	v_mfma_f32_16x16x32_bf16 v[48:51], v[64:67], v[94:97], v[48:51]
	v_and_b32_e32 v65, 0x4f, v80
	v_or_b32_e32 v66, s10, v65
	v_add_u32_e32 v64, s3, v81
	v_mfma_f32_16x16x32_bf16 v[12:15], v[90:93], v[68:71], v[12:15]
	v_ashrrev_i32_e32 v67, 31, v66
	v_ashrrev_i32_e32 v65, 31, v64
	v_lshlrev_b64 v[64:65], 1, v[64:65]
	v_mfma_f32_16x16x32_bf16 v[44:47], v[72:75], v[68:71], v[44:47]
	v_mfma_f32_16x16x32_bf16 v[28:31], v[82:85], v[68:71], v[28:31]
	v_lshlrev_b64 v[68:69], 11, v[66:67]
	v_lshl_add_u64 v[68:69], s[72:73], 0, v[68:69]
	v_lshrrev_b32_e32 v67, 1, v80
	v_lshl_add_u64 v[68:69], v[68:69], 0, v[64:65]
	v_and_b32_e32 v192, 24, v67
	v_lshl_add_u64 v[68:69], v[68:69], 0, v[192:193]
	v_cvt_pk_bf16_f32 v12, v12, v13
	v_cvt_pk_bf16_f32 v13, v14, v15
	global_store_dwordx2 v[68:69], v[12:13], off offset:96
	v_or_b32_e32 v12, 16, v66
	v_mfma_f32_16x16x32_bf16 v[8:11], v[90:93], v[76:79], v[8:11]
	v_ashrrev_i32_e32 v13, 31, v12
	v_lshlrev_b64 v[12:13], 11, v[12:13]
	v_lshl_add_u64 v[12:13], s[72:73], 0, v[12:13]
	v_lshl_add_u64 v[12:13], v[12:13], 0, v[64:65]
	v_lshl_add_u64 v[12:13], v[12:13], 0, v[192:193]
	s_nop 2
	v_cvt_pk_bf16_f32 v8, v8, v9
	v_cvt_pk_bf16_f32 v9, v10, v11
	global_store_dwordx2 v[12:13], v[8:9], off offset:96
	v_or_b32_e32 v8, 32, v66
	v_mfma_f32_16x16x32_bf16 v[4:7], v[90:93], v[86:89], v[4:7]
	v_ashrrev_i32_e32 v9, 31, v8
	v_lshlrev_b64 v[8:9], 11, v[8:9]
	v_lshl_add_u64 v[8:9], s[72:73], 0, v[8:9]
	v_lshl_add_u64 v[8:9], v[8:9], 0, v[64:65]
	v_lshl_add_u64 v[8:9], v[8:9], 0, v[192:193]
	s_nop 2
	v_cvt_pk_bf16_f32 v4, v4, v5
	v_cvt_pk_bf16_f32 v5, v6, v7
	global_store_dwordx2 v[8:9], v[4:5], off offset:96
	v_or_b32_e32 v4, 48, v66
	v_ashrrev_i32_e32 v5, 31, v4
	v_mfma_f32_16x16x32_bf16 v[40:43], v[72:75], v[76:79], v[40:43]
	v_lshlrev_b64 v[4:5], 11, v[4:5]
	v_lshl_add_u64 v[4:5], s[72:73], 0, v[4:5]
	v_lshl_add_u64 v[4:5], v[4:5], 0, v[64:65]
	v_mfma_f32_16x16x32_bf16 v[36:39], v[72:75], v[86:89], v[36:39]
	v_cvt_pk_bf16_f32 v14, v56, v57
	v_cvt_pk_bf16_f32 v15, v58, v59
	v_cvt_pk_bf16_f32 v10, v52, v53
	v_mfma_f32_16x16x32_bf16 v[32:35], v[72:75], v[94:97], v[32:35]
	v_cvt_pk_bf16_f32 v11, v54, v55
	v_lshl_add_u64 v[4:5], v[4:5], 0, v[192:193]
	v_cvt_pk_bf16_f32 v6, v48, v49
	v_mfma_f32_16x16x32_bf16 v[24:27], v[82:85], v[76:79], v[24:27]
	v_cvt_pk_bf16_f32 v7, v50, v51
	global_store_dwordx2 v[12:13], v[14:15], off
	v_cvt_pk_bf16_f32 v14, v40, v41
	v_mfma_f32_16x16x32_bf16 v[20:23], v[82:85], v[86:89], v[20:23]
	v_cvt_pk_bf16_f32 v15, v42, v43
	global_store_dwordx2 v[8:9], v[10:11], off
	v_cvt_pk_bf16_f32 v10, v36, v37
	v_mfma_f32_16x16x32_bf16 v[16:19], v[82:85], v[94:97], v[16:19]
	v_cvt_pk_bf16_f32 v11, v38, v39
	global_store_dwordx2 v[4:5], v[6:7], off
	v_cvt_pk_bf16_f32 v6, v32, v33
	v_mfma_f32_16x16x32_bf16 v[0:3], v[90:93], v[94:97], v[0:3]
	v_cvt_pk_bf16_f32 v7, v34, v35
	v_cvt_pk_bf16_f32 v44, v44, v45
	v_cvt_pk_bf16_f32 v45, v46, v47
	v_cvt_pk_bf16_f32 v28, v28, v29
	v_cvt_pk_bf16_f32 v29, v30, v31
	global_store_dwordx2 v[12:13], v[14:15], off offset:32
	v_cvt_pk_bf16_f32 v14, v24, v25
	v_cvt_pk_bf16_f32 v15, v26, v27
	global_store_dwordx2 v[8:9], v[10:11], off offset:32
	v_cvt_pk_bf16_f32 v10, v20, v21
	v_cvt_pk_bf16_f32 v11, v22, v23
	global_store_dwordx2 v[4:5], v[6:7], off offset:32
	v_cvt_pk_bf16_f32 v6, v16, v17
	v_cvt_pk_bf16_f32 v7, v18, v19
	v_cvt_pk_bf16_f32 v0, v0, v1
	v_cvt_pk_bf16_f32 v1, v2, v3
	global_store_dwordx2 v[68:69], v[60:61], off
	global_store_dwordx2 v[68:69], v[44:45], off offset:32
	global_store_dwordx2 v[68:69], v[28:29], off offset:64
	global_store_dwordx2 v[12:13], v[14:15], off offset:64
	global_store_dwordx2 v[8:9], v[10:11], off offset:64
	global_store_dwordx2 v[4:5], v[6:7], off offset:64
	global_store_dwordx2 v[4:5], v[0:1], off offset:96
	s_cbranch_scc0 .LBB0_79

.LBB0_253:
	s_min_i32 s2, s3, 8
	s_lshl_b32 s12, s2, 4
	s_mov_b32 s10, s8
	s_add_i32 s1, s1, 8
	s_add_i32 s3, s3, -8
	s_add_i32 s0, s0, -8
	s_sub_i32 s8, s8, s12
	s_cmp_ge_i32 s10, s12
	s_cbranch_scc1 .LBB0_253
	s_lshl_b32 s3, s2, 3
	s_abs_i32 s8, s3
	v_cvt_f32_u32_e32 v0, s8
	s_sub_i32 s16, 0, s8
	s_abs_i32 s13, s10
	s_xor_b32 s12, s10, s3
	v_rcp_iflag_f32_e32 v0, v0
	s_ashr_i32 s12, s12, 31
	v_mov_b32_e32 v81, v220
	v_mul_f32_e32 v0, 0x4f7ffffe, v0
	v_cvt_u32_f32_e32 v0, v0
	v_ashrrev_i32_e32 v16, 6, v81
	v_bfe_u32 v80, v81, 4, 2
	v_bfe_u32 v17, v81, 3, 3
	v_readfirstlane_b32 s17, v0
	s_mul_i32 s16, s16, s17
	s_mul_hi_u32 s16, s17, s16
	s_add_i32 s17, s17, s16
	s_mul_hi_u32 s16, s13, s17
	s_mul_i32 s17, s16, s8
	s_sub_i32 s13, s13, s17
	s_add_i32 s18, s16, 1
	s_sub_i32 s17, s13, s8
	s_cmp_ge_u32 s13, s8
	s_cselect_b32 s16, s18, s16
	s_cselect_b32 s13, s17, s13
	s_add_i32 s17, s16, 1
	s_cmp_ge_u32 s13, s8
	s_cselect_b32 s13, s17, s16
	s_abs_i32 s17, s2
	v_cvt_f32_u32_e32 v0, s17
	s_xor_b32 s16, s13, s12
	s_sub_i32 s13, 0, s17
	s_sub_i32 s18, s16, s12
	v_rcp_iflag_f32_e32 v0, v0
	s_mul_i32 s3, s18, s3
	s_sub_i32 s3, s10, s3
	s_abs_i32 s28, s3
	v_mul_f32_e32 v0, 0x4f7ffffe, v0
	v_cvt_u32_f32_e32 v0, v0
	s_xor_b32 s19, s3, s2
	s_ashr_i32 s19, s19, 31
	v_lshlrev_b32_e32 v18, 5, v16
	v_readfirstlane_b32 s29, v0
	s_mul_i32 s13, s13, s29
	s_mul_hi_u32 s13, s29, s13
	s_add_i32 s29, s29, s13
	s_mul_hi_u32 s13, s28, s29
	s_mul_i32 s29, s13, s17
	s_sub_i32 s28, s28, s29
	s_add_i32 s38, s13, 1
	s_sub_i32 s29, s28, s17
	s_cmp_ge_u32 s28, s17
	s_cselect_b32 s13, s38, s13
	s_cselect_b32 s28, s29, s28
	s_add_i32 s29, s13, 1
	s_cmp_ge_u32 s28, s17
	s_cselect_b32 s13, s29, s13
	s_xor_b32 s17, s13, s19
	s_sub_i32 s13, s17, s19
	s_mul_i32 s2, s13, s2
	s_add_i32 s3, s3, s1
	s_sub_i32 s3, s3, s2
	s_lshl_b32 s2, s18, 10
	s_lshl_b32 s13, s13, 7
	v_xor_b32_e32 v0, v80, v81
	s_add_i32 s2, s13, s2
	v_or_b32_e32 v1, v18, v17
	v_lshlrev_b32_e32 v0, 3, v0
	v_add_u32_e32 v2, s2, v1
	v_and_b32_e32 v19, 56, v0
	v_or_b32_e32 v3, 8, v1
	v_lshl_or_b32 v192, v2, 10, v19
	v_lshrrev_b32_e32 v2, 1, v3
	s_lshl_b32 s13, s3, 10
	v_readlane_b32 s3, v252, 39
	v_xor_b32_e32 v2, v2, v81
	s_or_b32 s3, s13, s3
	v_lshlrev_b32_e32 v2, 3, v2
	v_add_u32_e32 v4, s2, v3
	v_and_b32_e32 v20, 56, v2
	v_add_u32_e32 v3, s3, v3
	v_lshl_or_b32 v2, v4, 10, v20
	v_lshl_or_b32 v4, v3, 10, v20
	v_or_b32_e32 v3, 16, v1
	v_add_u32_e32 v0, s3, v1
	s_waitcnt lgkmcnt(0)
	v_add_u32_e32 v5, s2, v3
	v_add_u32_e32 v3, s3, v3
	v_or_b32_e32 v1, 24, v1
	v_lshl_or_b32 v8, v3, 10, v19
	v_lshrrev_b32_e32 v3, 1, v1
	v_xor_b32_e32 v3, v3, v81
	s_cmp_lg_u32 32, -1
	v_lshlrev_b32_e32 v3, 3, v3
	v_lshlrev_b32_e32 v22, 12, v16
	s_cselect_b32 s18, 32, 0
	v_lshl_or_b32 v6, v5, 10, v19
	v_add_u32_e32 v5, s2, v1
	v_and_b32_e32 v21, 56, v3
	v_add_u32_e32 v1, s3, v1
	v_add_u32_e32 v85, s18, v22
	s_add_i32 s28, s18, 0x4000
	v_lshl_or_b32 v12, v1, 10, v21
	v_ashrrev_i32_e32 v1, 1, v81
	v_add_u32_e32 v3, s28, v22
	v_readfirstlane_b32 s28, v85
	v_lshl_or_b32 v0, v0, 10, v19
	v_and_b32_e32 v83, 0xffffffc0, v1
	v_lshl_add_u64 v[14:15], v[192:193], 1, s[96:97]
	s_mov_b32 m0, s28
	v_mov_b32_e32 v1, v193
	v_readfirstlane_b32 s28, v3
	global_load_lds_dwordx4 v[14:15], off
	v_lshl_add_u64 v[0:1], v[0:1], 1, s[74:75]
	s_mov_b32 m0, s28
	v_mov_b32_e32 v3, v193
	s_add_i32 s28, s18, 0x400
	global_load_lds_dwordx4 v[0:1], off
	v_lshl_add_u64 v[0:1], v[2:3], 1, s[96:97]
	v_add_u32_e32 v2, s28, v22
	v_lshl_or_b32 v10, v5, 10, v21
	v_readfirstlane_b32 s28, v2
	s_mov_b32 m0, s28
	s_add_i32 s28, s18, 0x4400
	v_add_u32_e32 v2, s28, v22
	global_load_lds_dwordx4 v[0:1], off
	v_readfirstlane_b32 s28, v2
	s_mov_b32 m0, s28
	s_add_i32 s28, s18, 0x800
	v_mov_b32_e32 v5, v193
	v_add_u32_e32 v2, s28, v22
	v_lshl_add_u64 v[0:1], v[4:5], 1, s[74:75]
	v_readfirstlane_b32 s28, v2
	global_load_lds_dwordx4 v[0:1], off
	s_mov_b32 m0, s28
	s_add_i32 s28, s18, 0x4800
	v_mov_b32_e32 v7, v193
	v_add_u32_e32 v2, s28, v22
	v_lshl_add_u64 v[0:1], v[6:7], 1, s[96:97]
	v_readfirstlane_b32 s28, v2
	global_load_lds_dwordx4 v[0:1], off
	s_mov_b32 m0, s28
	s_add_i32 s28, s18, 0xc00
	v_mov_b32_e32 v9, v193
	v_add_u32_e32 v2, s28, v22
	s_addk_i32 s18, 0x4c00
	v_lshl_add_u64 v[0:1], v[8:9], 1, s[74:75]
	v_mov_b32_e32 v11, v193
	v_readfirstlane_b32 s28, v2
	v_add_u32_e32 v2, s18, v22
	global_load_lds_dwordx4 v[0:1], off
	v_lshl_add_u64 v[0:1], v[10:11], 1, s[96:97]
	s_mov_b32 m0, s28
	v_mov_b32_e32 v13, v193
	v_readfirstlane_b32 s18, v2
	global_load_lds_dwordx4 v[0:1], off
	v_lshl_add_u64 v[0:1], v[12:13], 1, s[74:75]
	s_mov_b32 m0, s18
	s_lshl_b32 s18, s16, 10
	global_load_lds_dwordx4 v[0:1], off
	v_bfe_u32 v0, v81, 1, 3
	s_lshl_b32 s28, s17, 7
	v_xor_b32_e32 v1, v80, v0
	v_bitop3_b32 v0, v80, v0, 4 bitop3:0x36
	s_add_i32 s28, s28, s18
	v_lshlrev_b32_e32 v86, 4, v0
	v_or_b32_e32 v0, s28, v17
	v_add_u32_e32 v0, v0, v18
	s_lshl_b32 s18, s19, 7
	v_subrev_u32_e32 v0, s18, v0
	s_lshl_b32 s18, s12, 10
	v_subrev_u32_e32 v0, s18, v0
	s_lshl_b32 s18, s16, 20
	s_lshl_b32 s28, s17, 17
	v_lshl_or_b32 v192, v0, 10, v19
	v_lshlrev_b32_e32 v0, 15, v16
	s_add_i32 s18, s18, s28
	v_lshlrev_b32_e32 v87, 4, v1
	v_lshlrev_b32_e32 v1, 10, v17
	v_add_u32_e32 v2, s18, v0
	v_or_b32_e32 v2, v2, v1
	s_add_i32 s1, s10, s1
	s_lshl_b32 s10, s12, 3
	v_or3_b32 v3, v2, v20, s33
	s_lshl_b32 s18, s19, 17
	s_add_i32 s19, s19, s10
	v_subrev_u32_e32 v3, s18, v3
	s_lshl_b32 s28, s12, 20
	s_sub_i32 s10, s19, s17
	s_lshl_b32 s12, s16, 3
	v_lshl_add_u64 v[64:65], v[192:193], 1, s[68:69]
	v_subrev_u32_e32 v192, s28, v3
	v_or3_b32 v3, v2, v19, s30
	s_sub_i32 s10, s10, s12
	s_min_i32 s0, s0, 8
	v_subrev_u32_e32 v3, s18, v3
	v_or3_b32 v2, v2, v21, s67
	s_mul_i32 s10, s10, s0
	v_lshl_add_u64 v[66:67], v[192:193], 1, s[68:69]
	v_subrev_u32_e32 v192, s28, v3
	v_subrev_u32_e32 v2, s18, v2
	s_add_i32 s1, s1, s10
	v_lshl_add_u64 v[68:69], v[192:193], 1, s[68:69]
	v_subrev_u32_e32 v192, s28, v2
	v_add_u32_e32 v2, s31, v17
	s_lshl_b32 s0, s1, 10
	v_add3_u32 v2, v2, v18, s0
	v_lshl_add_u64 v[70:71], v[192:193], 1, s[68:69]
	v_lshl_or_b32 v192, v2, 10, v19
	v_add3_u32 v2, s58, v0, v1
	s_lshl_b32 s0, s1, 20
	v_lshl_add_u64 v[72:73], v[192:193], 1, s[56:57]
	v_add3_u32 v192, v2, v20, s0
	v_add3_u32 v2, s59, v0, v1
	v_readlane_b32 s1, v254, 34
	v_and_b32_e32 v84, 15, v81
	s_waitcnt vmcnt(0)
	v_lshl_add_u64 v[74:75], v[192:193], 1, s[56:57]
	v_add3_u32 v192, v2, v19, s0
	v_add3_u32 v0, s1, v0, v1
	v_or_b32_e32 v23, v83, v84
	v_lshlrev_b32_e32 v24, 7, v81
	v_lshl_add_u64 v[76:77], v[192:193], 1, s[56:57]
	v_add3_u32 v192, v0, v21, s0
	v_mov_b32_e32 v56, 0
	s_mov_b32 s8, 0
	v_and_b32_e32 v82, 63, v81
	v_lshlrev_b32_e32 v88, 7, v23
	v_and_b32_e32 v89, 0x2780, v24
	v_lshl_add_u64 v[78:79], v[192:193], 1, s[56:57]
	s_mov_b64 s[0:1], 0
	v_mov_b32_e32 v57, v56
	v_mov_b32_e32 v58, v56
	v_mov_b32_e32 v59, v56
	v_mov_b32_e32 v60, v56
	v_mov_b32_e32 v61, v56
	v_mov_b32_e32 v62, v56
	v_mov_b32_e32 v63, v56
	v_mov_b32_e32 v0, v56
	v_mov_b32_e32 v1, v56
	v_mov_b32_e32 v2, v56
	v_mov_b32_e32 v3, v56
	v_mov_b32_e32 v4, v56
	v_mov_b32_e32 v5, v56
	v_mov_b32_e32 v6, v56
	v_mov_b32_e32 v7, v56
	v_mov_b32_e32 v8, v56
	v_mov_b32_e32 v9, v56
	v_mov_b32_e32 v10, v56
	v_mov_b32_e32 v11, v56
	v_mov_b32_e32 v12, v56
	v_mov_b32_e32 v13, v56
	v_mov_b32_e32 v14, v56
	v_mov_b32_e32 v15, v56
	v_mov_b32_e32 v16, v56
	v_mov_b32_e32 v17, v56
	v_mov_b32_e32 v18, v56
	v_mov_b32_e32 v19, v56
	v_mov_b32_e32 v20, v56
	v_mov_b32_e32 v21, v56
	v_mov_b32_e32 v22, v56
	v_mov_b32_e32 v23, v56
	v_mov_b32_e32 v24, v56
	v_mov_b32_e32 v25, v56
	v_mov_b32_e32 v26, v56
	v_mov_b32_e32 v27, v56
	v_mov_b32_e32 v28, v56
	v_mov_b32_e32 v29, v56
	v_mov_b32_e32 v30, v56
	v_mov_b32_e32 v31, v56
	v_mov_b32_e32 v32, v56
	v_mov_b32_e32 v33, v56
	v_mov_b32_e32 v34, v56
	v_mov_b32_e32 v35, v56
	v_mov_b32_e32 v36, v56
	v_mov_b32_e32 v37, v56
	v_mov_b32_e32 v38, v56
	v_mov_b32_e32 v39, v56
	v_mov_b32_e32 v40, v56
	v_mov_b32_e32 v41, v56
	v_mov_b32_e32 v42, v56
	v_mov_b32_e32 v43, v56
	v_mov_b32_e32 v44, v56
	v_mov_b32_e32 v45, v56
	v_mov_b32_e32 v46, v56
	v_mov_b32_e32 v47, v56
	v_mov_b32_e32 v48, v56
	v_mov_b32_e32 v49, v56
	v_mov_b32_e32 v50, v56
	v_mov_b32_e32 v51, v56
	v_mov_b32_e32 v52, v56
	v_mov_b32_e32 v53, v56
	v_mov_b32_e32 v54, v56
	v_mov_b32_e32 v55, v56
	s_waitcnt vmcnt(0) lgkmcnt(0)
	s_barrier
	v_add_u32_e32 v134, 32, v88
	v_add_u32_e32 v135, 32, v89
	v_add_u32_e32 v132, v134, v87
	v_add_u32_e32 v133, v135, v87
	ds_read_b128 v[90:93], v132
	ds_read_b128 v[98:101], v132 offset:2048
	ds_read_b128 v[106:109], v132 offset:4096
	ds_read_b128 v[114:117], v132 offset:6144
	ds_read_b128 v[94:97], v133 offset:16384
	ds_read_b128 v[102:105], v133 offset:18432
	ds_read_b128 v[110:113], v133 offset:20480
	ds_read_b128 v[118:121], v133 offset:22528
	v_add_u32_e32 v128, 0x8000, v85
	s_nop 0
	v_readfirstlane_b32 s12, v128
	s_nop 1
	v_lshl_add_u64 v[130:131], v[64:65], 0, s[0:1]
	s_mov_b32 m0, s12
	s_nop 0
	global_load_lds_dwordx4 v[130:131], off
	v_lshl_add_u64 v[130:131], v[72:73], 0, s[0:1]
	s_add_i32 m0, s12, 0x4000
	s_nop 0
	global_load_lds_dwordx4 v[130:131], off
	v_lshl_add_u64 v[130:131], v[66:67], 0, s[0:1]
	s_add_i32 m0, s12, 0x400
	s_nop 0
	global_load_lds_dwordx4 v[130:131], off
	v_lshl_add_u64 v[130:131], v[74:75], 0, s[0:1]
	s_add_i32 m0, s12, 0x4400
	s_nop 0
	global_load_lds_dwordx4 v[130:131], off
	v_lshl_add_u64 v[130:131], v[68:69], 0, s[0:1]
	s_add_i32 m0, s12, 0x800
	s_nop 0
	global_load_lds_dwordx4 v[130:131], off
	v_lshl_add_u64 v[130:131], v[76:77], 0, s[0:1]
	s_add_i32 m0, s12, 0x4800
	s_nop 0
	global_load_lds_dwordx4 v[130:131], off
	v_lshl_add_u64 v[130:131], v[70:71], 0, s[0:1]
	s_add_i32 m0, s12, 0xc00
	s_nop 0
	global_load_lds_dwordx4 v[130:131], off
	v_lshl_add_u64 v[130:131], v[78:79], 0, s[0:1]
	s_add_i32 m0, s12, 0x4c00
	s_nop 0
	global_load_lds_dwordx4 v[130:131], off
	s_add_u32 s0, s0, 0x80
	s_addc_u32 s1, s1, 0
.Lg255_loop:
	s_and_b32 s10, s8, 0x8000
	s_xor_b32 s12, s10, 0x8000
	v_add_u32_e32 v132, v134, v86
	v_add_u32_e32 v133, v135, v86
	ds_read_b128 v[152:155], v132
	ds_read_b128 v[156:159], v132 offset:2048
	ds_read_b128 v[160:163], v132 offset:4096
	ds_read_b128 v[164:167], v132 offset:6144
	s_waitcnt lgkmcnt(4)
	v_mfma_f32_16x16x32_bf16 v[52:55], v[90:93], v[94:97], v[52:55]
	v_mfma_f32_16x16x32_bf16 v[48:51], v[90:93], v[102:105], v[48:51]
	v_mfma_f32_16x16x32_bf16 v[44:47], v[90:93], v[110:113], v[44:47]
	v_mfma_f32_16x16x32_bf16 v[40:43], v[90:93], v[118:121], v[40:43]
	ds_read_b128 v[168:171], v133 offset:16384
	ds_read_b128 v[172:175], v133 offset:18432
	ds_read_b128 v[176:179], v133 offset:20480
	ds_read_b128 v[180:183], v133 offset:22528
	v_mfma_f32_16x16x32_bf16 v[36:39], v[98:101], v[94:97], v[36:39]
	v_mfma_f32_16x16x32_bf16 v[32:35], v[98:101], v[102:105], v[32:35]
	v_mfma_f32_16x16x32_bf16 v[28:31], v[98:101], v[110:113], v[28:31]
	v_mfma_f32_16x16x32_bf16 v[24:27], v[98:101], v[118:121], v[24:27]
	v_mfma_f32_16x16x32_bf16 v[20:23], v[106:109], v[94:97], v[20:23]
	v_mfma_f32_16x16x32_bf16 v[16:19], v[106:109], v[102:105], v[16:19]
	v_mfma_f32_16x16x32_bf16 v[12:15], v[106:109], v[110:113], v[12:15]
	v_mfma_f32_16x16x32_bf16 v[8:11], v[106:109], v[118:121], v[8:11]
	v_mfma_f32_16x16x32_bf16 v[4:7], v[114:117], v[94:97], v[4:7]
	v_mfma_f32_16x16x32_bf16 v[0:3], v[114:117], v[102:105], v[0:3]
	v_mfma_f32_16x16x32_bf16 v[60:63], v[114:117], v[110:113], v[60:63]
	v_mfma_f32_16x16x32_bf16 v[56:59], v[114:117], v[118:121], v[56:59]
	s_waitcnt vmcnt(0) lgkmcnt(0)
	s_barrier
	v_add_u32_e32 v128, s10, v85
	s_add_i32 s10, s12, 32
	v_add_u32_e32 v134, s10, v88
	v_add_u32_e32 v135, s10, v89
	v_add_u32_e32 v132, v134, v87
	v_add_u32_e32 v133, v135, v87
	ds_read_b128 v[90:93], v132
	ds_read_b128 v[98:101], v132 offset:2048
	ds_read_b128 v[106:109], v132 offset:4096
	ds_read_b128 v[114:117], v132 offset:6144
	ds_read_b128 v[94:97], v133 offset:16384
	ds_read_b128 v[102:105], v133 offset:18432
	ds_read_b128 v[110:113], v133 offset:20480
	ds_read_b128 v[118:121], v133 offset:22528
	v_readfirstlane_b32 s12, v128
	v_mfma_f32_16x16x32_bf16 v[52:55], v[152:155], v[168:171], v[52:55]
	v_lshl_add_u64 v[130:131], v[64:65], 0, s[0:1]
	s_mov_b32 m0, s12
	s_nop 0
	global_load_lds_dwordx4 v[130:131], off
	v_mfma_f32_16x16x32_bf16 v[48:51], v[152:155], v[172:175], v[48:51]
	v_mfma_f32_16x16x32_bf16 v[44:47], v[152:155], v[176:179], v[44:47]
	v_lshl_add_u64 v[130:131], v[72:73], 0, s[0:1]
	s_add_i32 m0, s12, 0x4000
	s_nop 0
	global_load_lds_dwordx4 v[130:131], off
	v_mfma_f32_16x16x32_bf16 v[40:43], v[152:155], v[180:183], v[40:43]
	v_mfma_f32_16x16x32_bf16 v[36:39], v[156:159], v[168:171], v[36:39]
	v_lshl_add_u64 v[130:131], v[66:67], 0, s[0:1]
	s_add_i32 m0, s12, 0x400
	s_nop 0
	global_load_lds_dwordx4 v[130:131], off
	v_mfma_f32_16x16x32_bf16 v[32:35], v[156:159], v[172:175], v[32:35]
	v_mfma_f32_16x16x32_bf16 v[28:31], v[156:159], v[176:179], v[28:31]
	v_lshl_add_u64 v[130:131], v[74:75], 0, s[0:1]
	s_add_i32 m0, s12, 0x4400
	s_nop 0
	global_load_lds_dwordx4 v[130:131], off
	v_mfma_f32_16x16x32_bf16 v[24:27], v[156:159], v[180:183], v[24:27]
	v_mfma_f32_16x16x32_bf16 v[20:23], v[160:163], v[168:171], v[20:23]
	v_lshl_add_u64 v[130:131], v[68:69], 0, s[0:1]
	s_add_i32 m0, s12, 0x800
	s_nop 0
	global_load_lds_dwordx4 v[130:131], off
	v_mfma_f32_16x16x32_bf16 v[16:19], v[160:163], v[172:175], v[16:19]
	v_mfma_f32_16x16x32_bf16 v[12:15], v[160:163], v[176:179], v[12:15]
	v_lshl_add_u64 v[130:131], v[76:77], 0, s[0:1]
	s_add_i32 m0, s12, 0x4800
	s_nop 0
	global_load_lds_dwordx4 v[130:131], off
	v_mfma_f32_16x16x32_bf16 v[8:11], v[160:163], v[180:183], v[8:11]
	v_mfma_f32_16x16x32_bf16 v[4:7], v[164:167], v[168:171], v[4:7]
	v_lshl_add_u64 v[130:131], v[70:71], 0, s[0:1]
	s_add_i32 m0, s12, 0xc00
	s_nop 0
	global_load_lds_dwordx4 v[130:131], off
	v_mfma_f32_16x16x32_bf16 v[0:3], v[164:167], v[172:175], v[0:3]
	v_mfma_f32_16x16x32_bf16 v[60:63], v[164:167], v[176:179], v[60:63]
	v_lshl_add_u64 v[130:131], v[78:79], 0, s[0:1]
	s_add_i32 m0, s12, 0x4c00
	s_nop 0
	global_load_lds_dwordx4 v[130:131], off
	v_mfma_f32_16x16x32_bf16 v[56:59], v[164:167], v[180:183], v[56:59]
	s_add_i32 s8, s8, 0x8000
	s_add_u32 s0, s0, 0x80
	s_addc_u32 s1, s1, 0
	s_cmpk_lg_i32 s0, 0x780
	s_cbranch_scc1 .Lg255_loop
	s_and_b32 s10, s8, 0x8000
	s_xor_b32 s12, s10, 0x8000
	v_add_u32_e32 v132, v134, v86
	v_add_u32_e32 v133, v135, v86
	ds_read_b128 v[152:155], v132
	ds_read_b128 v[156:159], v132 offset:2048
	ds_read_b128 v[160:163], v132 offset:4096
	ds_read_b128 v[164:167], v132 offset:6144
	s_waitcnt lgkmcnt(4)
	v_mfma_f32_16x16x32_bf16 v[52:55], v[90:93], v[94:97], v[52:55]
	v_mfma_f32_16x16x32_bf16 v[48:51], v[90:93], v[102:105], v[48:51]
	v_mfma_f32_16x16x32_bf16 v[44:47], v[90:93], v[110:113], v[44:47]
	v_mfma_f32_16x16x32_bf16 v[40:43], v[90:93], v[118:121], v[40:43]
	ds_read_b128 v[168:171], v133 offset:16384
	ds_read_b128 v[172:175], v133 offset:18432
	ds_read_b128 v[176:179], v133 offset:20480
	ds_read_b128 v[180:183], v133 offset:22528
	v_mfma_f32_16x16x32_bf16 v[36:39], v[98:101], v[94:97], v[36:39]
	v_mfma_f32_16x16x32_bf16 v[32:35], v[98:101], v[102:105], v[32:35]
	v_mfma_f32_16x16x32_bf16 v[28:31], v[98:101], v[110:113], v[28:31]
	v_mfma_f32_16x16x32_bf16 v[24:27], v[98:101], v[118:121], v[24:27]
	v_mfma_f32_16x16x32_bf16 v[20:23], v[106:109], v[94:97], v[20:23]
	v_mfma_f32_16x16x32_bf16 v[16:19], v[106:109], v[102:105], v[16:19]
	v_mfma_f32_16x16x32_bf16 v[12:15], v[106:109], v[110:113], v[12:15]
	v_mfma_f32_16x16x32_bf16 v[8:11], v[106:109], v[118:121], v[8:11]
	v_mfma_f32_16x16x32_bf16 v[4:7], v[114:117], v[94:97], v[4:7]
	v_mfma_f32_16x16x32_bf16 v[0:3], v[114:117], v[102:105], v[0:3]
	v_mfma_f32_16x16x32_bf16 v[60:63], v[114:117], v[110:113], v[60:63]
	v_mfma_f32_16x16x32_bf16 v[56:59], v[114:117], v[118:121], v[56:59]
	s_waitcnt vmcnt(0) lgkmcnt(0)
	s_barrier
	v_mfma_f32_16x16x32_bf16 v[52:55], v[152:155], v[168:171], v[52:55]
	v_mfma_f32_16x16x32_bf16 v[48:51], v[152:155], v[172:175], v[48:51]
	v_mfma_f32_16x16x32_bf16 v[44:47], v[152:155], v[176:179], v[44:47]
	v_mfma_f32_16x16x32_bf16 v[40:43], v[152:155], v[180:183], v[40:43]
	v_mfma_f32_16x16x32_bf16 v[36:39], v[156:159], v[168:171], v[36:39]
	v_mfma_f32_16x16x32_bf16 v[32:35], v[156:159], v[172:175], v[32:35]
	v_mfma_f32_16x16x32_bf16 v[28:31], v[156:159], v[176:179], v[28:31]
	v_mfma_f32_16x16x32_bf16 v[24:27], v[156:159], v[180:183], v[24:27]
	v_mfma_f32_16x16x32_bf16 v[20:23], v[160:163], v[168:171], v[20:23]
	v_mfma_f32_16x16x32_bf16 v[16:19], v[160:163], v[172:175], v[16:19]
	v_mfma_f32_16x16x32_bf16 v[12:15], v[160:163], v[176:179], v[12:15]
	v_mfma_f32_16x16x32_bf16 v[8:11], v[160:163], v[180:183], v[8:11]
	v_mfma_f32_16x16x32_bf16 v[4:7], v[164:167], v[168:171], v[4:7]
	v_mfma_f32_16x16x32_bf16 v[0:3], v[164:167], v[172:175], v[0:3]
	v_mfma_f32_16x16x32_bf16 v[60:63], v[164:167], v[176:179], v[60:63]
	v_mfma_f32_16x16x32_bf16 v[56:59], v[164:167], v[180:183], v[56:59]
	v_add_u32_e32 v112, 32, v88
	v_add_u32_e32 v100, v112, v87
	ds_read_b128 v[92:95], v100 offset:36864
	ds_read_b128 v[64:67], v100 offset:32768
	ds_read_b128 v[72:75], v100 offset:38912
	ds_read_b128 v[100:103], v100 offset:34816
	v_add_u32_e32 v85, 32, v89
	v_add_u32_e32 v87, v85, v87
	ds_read_b128 v[88:91], v87 offset:53248
	ds_read_b128 v[68:71], v87 offset:55296
	ds_read_b128 v[76:79], v87 offset:49152
	ds_read_b128 v[96:99], v87 offset:51200
	s_waitcnt lgkmcnt(3)
	v_mfma_f32_16x16x32_bf16 v[108:111], v[92:95], v[88:91], v[12:15]
	v_and_or_b32 v81, v81, 64, s3
	s_movk_i32 s0, 0x3fff
	s_nop 0
	v_add_u32_e32 v12, v112, v86
	s_waitcnt lgkmcnt(1)
	v_mfma_f32_16x16x32_bf16 v[52:55], v[64:67], v[76:79], v[52:55]
	v_add_u32_e32 v13, v85, v86
	s_waitcnt lgkmcnt(0)
	v_mfma_f32_16x16x32_bf16 v[48:51], v[64:67], v[96:99], v[48:51]
	v_mfma_f32_16x16x32_bf16 v[104:107], v[64:67], v[88:91], v[44:47]
	v_mfma_f32_16x16x32_bf16 v[40:43], v[64:67], v[68:71], v[40:43]
	v_mfma_f32_16x16x32_bf16 v[36:39], v[100:103], v[76:79], v[36:39]
	v_mfma_f32_16x16x32_bf16 v[32:35], v[100:103], v[96:99], v[32:35]
	v_mfma_f32_16x16x32_bf16 v[64:67], v[100:103], v[88:91], v[28:31]
	v_mfma_f32_16x16x32_bf16 v[24:27], v[100:103], v[68:71], v[24:27]
	v_mfma_f32_16x16x32_bf16 v[100:103], v[92:95], v[76:79], v[20:23]
	v_mfma_f32_16x16x32_bf16 v[16:19], v[92:95], v[96:99], v[16:19]
	v_mfma_f32_16x16x32_bf16 v[8:11], v[92:95], v[68:71], v[8:11]
	v_mfma_f32_16x16x32_bf16 v[76:79], v[72:75], v[76:79], v[4:7]
	v_mfma_f32_16x16x32_bf16 v[0:3], v[72:75], v[96:99], v[0:3]
	v_mfma_f32_16x16x32_bf16 v[88:91], v[72:75], v[88:91], v[60:63]
	v_mfma_f32_16x16x32_bf16 v[68:71], v[72:75], v[68:71], v[56:59]
	ds_read_b128 v[4:7], v12 offset:32768
	ds_read_b128 v[96:99], v12 offset:36864
	ds_read_b128 v[116:119], v12 offset:38912
	ds_read_b128 v[56:59], v12 offset:34816
	ds_read_b128 v[72:75], v13 offset:49152
	ds_read_b128 v[92:95], v13 offset:51200
	ds_read_b128 v[112:115], v13 offset:53248
	ds_read_b128 v[120:123], v13 offset:55296
	s_waitcnt lgkmcnt(3)
	v_mfma_f32_16x16x32_bf16 v[60:63], v[4:7], v[72:75], v[52:55]
	s_waitcnt vmcnt(0)
	s_waitcnt lgkmcnt(0)
	s_barrier
	v_mfma_f32_16x16x32_bf16 v[44:47], v[4:7], v[92:95], v[48:51]
	v_mfma_f32_16x16x32_bf16 v[28:31], v[4:7], v[112:115], v[104:107]
	v_mfma_f32_16x16x32_bf16 v[12:15], v[4:7], v[120:123], v[40:43]
	v_mfma_f32_16x16x32_bf16 v[52:55], v[56:59], v[72:75], v[36:39]
	v_mfma_f32_16x16x32_bf16 v[36:39], v[56:59], v[92:95], v[32:35]
	v_mfma_f32_16x16x32_bf16 v[20:23], v[56:59], v[112:115], v[64:67]
	v_mfma_f32_16x16x32_bf16 v[4:7], v[56:59], v[120:123], v[24:27]
	s_nop 1
	v_or_b32_e32 v66, v81, v84
	v_cmp_lt_i32_e32 vcc, s0, v66
	v_mfma_f32_16x16x32_bf16 v[56:59], v[96:99], v[72:75], v[100:103]
	v_mfma_f32_16x16x32_bf16 v[40:43], v[96:99], v[92:95], v[16:19]
	v_mfma_f32_16x16x32_bf16 v[24:27], v[96:99], v[112:115], v[108:111]
	v_mfma_f32_16x16x32_bf16 v[8:11], v[96:99], v[120:123], v[8:11]
	v_mfma_f32_16x16x32_bf16 v[48:51], v[116:119], v[72:75], v[76:79]
	v_mfma_f32_16x16x32_bf16 v[32:35], v[116:119], v[92:95], v[0:3]
	v_mfma_f32_16x16x32_bf16 v[16:19], v[116:119], v[112:115], v[88:91]
	v_mfma_f32_16x16x32_bf16 v[0:3], v[116:119], v[120:123], v[68:71]
	s_and_saveexec_b64 s[0:1], vcc
	s_xor_b64 s[0:1], exec, s[0:1]
	s_addk_i32 s3, 0xc000
	s_lshr_b32 s3, s3, 8
	v_and_b32_e32 v64, 0xcf, v66
	v_or_b32_e32 v192, 0x2000, v64
	v_mov_b32_e32 v65, s3
	s_andn2_saveexec_b64 s[0:1], s[0:1]
	s_ashr_i32 s3, s13, 13
	v_and_b32_e32 v192, 0x1fcf, v66
	v_mov_b32_e32 v65, s3
	s_or_b64 exec, exec, s[0:1]
	v_add_u32_e32 v64, s2, v83
	s_movk_i32 s0, 0x17f
	v_cmp_lt_i32_e64 s[48:49], s0, v64
	s_movk_i32 s0, 0x480
	s_movk_i32 s2, 0x780
	v_subrev_co_u32_e32 v67, vcc, 0x380, v64
	v_cmp_gt_u32_e64 s[42:43], s0, v64
	s_movk_i32 s0, 0x47f
	v_cmp_eq_u32_e64 s[2:3], s2, v64
	s_xor_b64 s[88:89], vcc, -1
	v_cmp_lt_u32_e32 vcc, s0, v64
	v_and_b32_e32 v68, 0x7fffff80, v64
	s_movk_i32 s0, 0x700
	v_writelane_b32 v255, s2, 20
	v_cmp_ne_u32_e64 s[0:1], s0, v68
	s_and_b64 s[14:15], vcc, s[0:1]
	v_writelane_b32 v255, s3, 21
	s_movk_i32 s2, 0x680
	v_subrev_co_u32_e32 v68, vcc, 0x700, v64
	v_cmp_gt_u32_e64 s[44:45], s2, v64
	s_movk_i32 s2, 0x280
	v_mov_b32_e32 v69, 0xfffff980
	v_mov_b32_e32 v70, 0xfffffb80
	v_ashrrev_i32_e32 v78, 6, v68
	v_lshrrev_b32_e32 v79, 6, v67
	v_mov_b32_e32 v67, 0xfffffd80
	v_mov_b32_e32 v68, 0xfffffe80
	v_cmp_gt_u32_e64 s[40:41], s2, v64
	v_cndmask_b32_e64 v69, v69, v70, s[44:45]
	v_add_u32_e32 v69, v69, v64
	v_cndmask_b32_e64 v67, v67, v68, s[40:41]
	v_add_u32_e32 v67, v67, v64
	s_xor_b64 s[0:1], vcc, -1
	v_lshlrev_b32_e32 v76, 3, v80
	v_lshlrev_b32_e32 v74, 2, v80
	v_lshrrev_b32_e32 v75, 6, v69
	v_ashrrev_i32_e32 v77, 5, v67
	v_cmp_gt_u32_e64 s[38:39], 16, v82
	s_and_saveexec_b64 s[2:3], s[48:49]
	s_xor_b64 s[90:91], exec, s[2:3]
	s_cbranch_execz .LBB0_286
	v_cmp_gt_u32_e64 s[50:51], s33, v192
	s_and_saveexec_b64 s[2:3], s[88:89]
	s_xor_b64 s[92:93], exec, s[2:3]
	s_cbranch_execz .LBB0_279
	s_and_saveexec_b64 s[2:3], s[14:15]
	s_xor_b64 s[94:95], exec, s[2:3]
	s_cbranch_execz .LBB0_276
	s_and_saveexec_b64 s[2:3], s[0:1]
	s_xor_b64 s[46:47], exec, s[2:3]
	s_cbranch_execz .LBB0_269
	s_mov_b64 vcc, exec
	v_readlane_b32 s2, v255, 20
	v_readlane_b32 s3, v255, 21
	s_and_b64 s[2:3], vcc, s[2:3]
	s_mov_b64 exec, s[2:3]
	s_cbranch_execz .LBB0_268
	s_and_saveexec_b64 s[2:3], s[50:51]
	s_cbranch_execz .LBB0_267
	v_readlane_b32 s16, v254, 9
	v_lshlrev_b32_e32 v48, 7, v192
	v_mov_b32_e32 v49, v193
	v_readlane_b32 s24, v254, 17
	v_readlane_b32 s25, v254, 18
	v_lshlrev_b32_e32 v50, 2, v76
	v_mov_b32_e32 v51, v193
	v_lshl_add_u64 v[48:49], s[24:25], 0, v[48:49]
	v_lshl_add_u64 v[56:57], v[48:49], 0, v[50:51]
	global_load_dwordx4 v[48:51], v[56:57], off
	s_nop 0
	global_load_dwordx4 v[56:59], v[56:57], off offset:16
	v_readlane_b32 s30, v254, 23
	v_readlane_b32 s31, v254, 24
	s_movk_i32 s30, 0x4000
	s_mov_b32 s31, s9
	v_readlane_b32 s17, v254, 10
	v_readlane_b32 s18, v254, 11
	v_readlane_b32 s19, v254, 12
	v_readlane_b32 s20, v254, 13
	v_readlane_b32 s21, v254, 14
	v_readlane_b32 s22, v254, 15
	v_readlane_b32 s23, v254, 16
	v_readlane_b32 s26, v254, 19
	v_readlane_b32 s27, v254, 20
	v_readlane_b32 s28, v254, 21
	v_readlane_b32 s29, v254, 22
	s_waitcnt vmcnt(1)
	v_mov_b32_e32 v68, v49
	s_waitcnt vmcnt(0)
	v_mov_b32_e32 v70, v57
	v_mov_b32_e32 v71, v59
	v_mov_b32_e32 v69, v51
	v_mov_b32_e32 v57, v58
	v_mov_b32_e32 v49, v50
	v_pk_mul_f32 v[50:51], v[54:55], v[70:71]
	v_pk_mul_f32 v[58:59], v[52:53], v[68:69]
	v_pk_mul_f32 v[52:53], v[52:53], v[48:49]
	v_pk_mul_f32 v[54:55], v[54:55], v[56:57]
	v_pk_fma_f32 v[50:51], v[62:63], v[56:57], v[50:51] neg_lo:[0,0,1] neg_hi:[0,0,1]
	v_pk_fma_f32 v[48:49], v[60:61], v[48:49], v[58:59] neg_lo:[0,0,1] neg_hi:[0,0,1]
	v_pk_fma_f32 v[54:55], v[62:63], v[70:71], v[54:55]
	v_pk_fma_f32 v[52:53], v[60:61], v[68:69], v[52:53]
	v_mov_b64_e32 v[62:63], v[50:51]
	v_mov_b64_e32 v[60:61], v[48:49]
